# first K-loop trip peeled in the seven 8-phase GEMM loops (C = inline 0), per-tile v_mov zero blocks removed
# speedup vs baseline: 1.0080x; 1.0080x over previous
.LBB0_32:
	s_add_u32 s50, s46, 0x100
	s_addc_u32 s51, s47, 0
	s_mov_b32 s52, -2
	s_add_u32 s0, s30, 0x100
	s_addc_u32 s1, s31, 0
	s_add_i32 s42, 0, 0x10000
	v_add_u32_e32 v96, s42, v229
	ds_read_b128 v[98:101], v96
	ds_read_b128 v[102:105], v96 offset:1024
	ds_read_b128 v[106:109], v96 offset:2048
	ds_read_b128 v[110:113], v96 offset:3072
	s_cmp_eq_u32 s52, 40
	s_cselect_b32 s47, s61, s1
	s_cselect_b32 s46, s60, s0
	s_cselect_b32 s45, s69, s51
	s_cselect_b32 s44, s68, s50
	v_lshl_add_u64 v[138:139], s[30:31], 0, v[146:147]
	s_add_i32 m0, s70, 0xc000
	ds_read_b128 v[114:117], v230
	ds_read_b128 v[118:121], v230 offset:1024
	ds_read_b128 v[122:125], v230 offset:2048
	ds_read_b128 v[126:129], v230 offset:3072
	ds_read_b128 v[130:133], v230 offset:4096
	ds_read_b128 v[134:137], v230 offset:5120
	global_load_lds_dwordx4 v[138:139], off
	v_lshl_add_u64 v[138:139], s[30:31], 0, v[148:149]
	s_add_i32 m0, s70, 0xe000
	s_nop 0
	global_load_lds_dwordx4 v[138:139], off
	s_waitcnt lgkmcnt(6)
	s_barrier
	s_waitcnt lgkmcnt(0)
	s_setprio 1
	s_waitcnt lgkmcnt(0)
	v_mfma_f32_16x16x32_bf16 v[92:95], v[98:101], v[114:117], 0
	v_mfma_f32_16x16x32_bf16 v[68:71], v[106:109], v[114:117], 0
	v_mfma_f32_16x16x32_bf16 v[88:91], v[98:101], v[122:125], 0
	v_mfma_f32_16x16x32_bf16 v[64:67], v[106:109], v[122:125], 0
	v_mfma_f32_16x16x32_bf16 v[84:87], v[98:101], v[130:133], 0
	v_mfma_f32_16x16x32_bf16 v[60:63], v[106:109], v[130:133], 0
	v_mfma_f32_16x16x32_bf16 v[92:95], v[102:105], v[118:121], v[92:95]
	v_mfma_f32_16x16x32_bf16 v[68:71], v[110:113], v[118:121], v[68:71]
	v_mfma_f32_16x16x32_bf16 v[88:91], v[102:105], v[126:129], v[88:91]
	v_mfma_f32_16x16x32_bf16 v[64:67], v[110:113], v[126:129], v[64:67]
	v_mfma_f32_16x16x32_bf16 v[84:87], v[102:105], v[134:137], v[84:87]
	v_mfma_f32_16x16x32_bf16 v[60:63], v[110:113], v[134:137], v[60:63]
	s_setprio 0
	s_barrier
	s_add_i32 s43, 0, 0x14000
	s_add_i32 s30, s42, s37
	v_add_u32_e32 v96, s43, v229
	v_lshl_add_u64 v[162:163], s[44:45], 0, v[144:145]
	s_mov_b32 m0, s30
	ds_read_b128 v[138:141], v96
	ds_read_b128 v[150:153], v96 offset:1024
	ds_read_b128 v[154:157], v96 offset:2048
	ds_read_b128 v[158:161], v96 offset:3072
	global_load_lds_dwordx4 v[162:163], off
	v_lshl_add_u64 v[164:165], s[44:45], 0, v[142:143]
	s_add_i32 m0, s30, 0x2000
	s_nop 0
	global_load_lds_dwordx4 v[164:165], off
	s_barrier
	s_waitcnt lgkmcnt(0)
	s_setprio 1
	s_waitcnt lgkmcnt(0)
	v_mfma_f32_16x16x32_bf16 v[48:51], v[138:141], v[114:117], 0
	v_mfma_f32_16x16x32_bf16 v[20:23], v[154:157], v[114:117], 0
	v_mfma_f32_16x16x32_bf16 v[40:43], v[138:141], v[122:125], 0
	v_mfma_f32_16x16x32_bf16 v[16:19], v[154:157], v[122:125], 0
	v_mfma_f32_16x16x32_bf16 v[36:39], v[138:141], v[130:133], 0
	v_mfma_f32_16x16x32_bf16 v[12:15], v[154:157], v[130:133], 0
	v_mfma_f32_16x16x32_bf16 v[48:51], v[150:153], v[118:121], v[48:51]
	v_mfma_f32_16x16x32_bf16 v[20:23], v[158:161], v[118:121], v[20:23]
	v_mfma_f32_16x16x32_bf16 v[40:43], v[150:153], v[126:129], v[40:43]
	v_mfma_f32_16x16x32_bf16 v[16:19], v[158:161], v[126:129], v[16:19]
	v_mfma_f32_16x16x32_bf16 v[36:39], v[150:153], v[134:137], v[36:39]
	v_mfma_f32_16x16x32_bf16 v[12:15], v[158:161], v[134:137], v[12:15]
	s_setprio 0
	s_mov_b32 m0, s70
	v_lshl_add_u64 v[166:167], s[46:47], 0, v[144:145]
	s_barrier
	ds_read_b128 v[114:117], v230 offset:16384
	ds_read_b128 v[118:121], v230 offset:17408
	ds_read_b128 v[122:125], v230 offset:18432
	ds_read_b128 v[126:129], v230 offset:19456
	ds_read_b128 v[130:133], v230 offset:20480
	ds_read_b128 v[134:137], v230 offset:21504
	global_load_lds_dwordx4 v[166:167], off
	v_lshl_add_u64 v[168:169], s[46:47], 0, v[142:143]
	s_mov_b32 m0, s71
	s_nop 0
	global_load_lds_dwordx4 v[168:169], off
	s_barrier
	s_waitcnt lgkmcnt(0)
	s_setprio 1
	s_waitcnt lgkmcnt(0)
	v_mfma_f32_16x16x32_bf16 v[80:83], v[98:101], v[114:117], 0
	v_mfma_f32_16x16x32_bf16 v[56:59], v[106:109], v[114:117], 0
	v_mfma_f32_16x16x32_bf16 v[76:79], v[98:101], v[122:125], 0
	v_mfma_f32_16x16x32_bf16 v[52:55], v[106:109], v[122:125], 0
	v_mfma_f32_16x16x32_bf16 v[72:75], v[98:101], v[130:133], 0
	v_mfma_f32_16x16x32_bf16 v[44:47], v[106:109], v[130:133], 0
	v_mfma_f32_16x16x32_bf16 v[80:83], v[102:105], v[118:121], v[80:83]
	v_mfma_f32_16x16x32_bf16 v[56:59], v[110:113], v[118:121], v[56:59]
	v_mfma_f32_16x16x32_bf16 v[76:79], v[102:105], v[126:129], v[76:79]
	v_mfma_f32_16x16x32_bf16 v[52:55], v[110:113], v[126:129], v[52:55]
	v_mfma_f32_16x16x32_bf16 v[72:75], v[102:105], v[134:137], v[72:75]
	v_mfma_f32_16x16x32_bf16 v[44:47], v[110:113], v[134:137], v[44:47]
	s_setprio 0
	s_barrier
	s_add_u32 s30, s44, 0xb0000
	s_addc_u32 s31, s45, 0
	s_add_i32 s42, s43, s37
	v_lshl_add_u64 v[98:99], s[30:31], 0, v[144:145]
	s_mov_b32 m0, s42
	s_nop 0
	global_load_lds_dwordx4 v[98:99], off
	v_lshl_add_u64 v[98:99], s[30:31], 0, v[142:143]
	s_add_i32 m0, s42, 0x2000
	s_nop 0
	global_load_lds_dwordx4 v[98:99], off
	s_waitcnt vmcnt(6)
	s_barrier
	s_setprio 1
	v_mfma_f32_16x16x32_bf16 v[32:35], v[138:141], v[114:117], 0
	v_mfma_f32_16x16x32_bf16 v[8:11], v[154:157], v[114:117], 0
	v_mfma_f32_16x16x32_bf16 v[28:31], v[138:141], v[122:125], 0
	v_mfma_f32_16x16x32_bf16 v[4:7], v[154:157], v[122:125], 0
	v_mfma_f32_16x16x32_bf16 v[24:27], v[138:141], v[130:133], 0
	v_mfma_f32_16x16x32_bf16 v[0:3], v[154:157], v[130:133], 0
	v_mfma_f32_16x16x32_bf16 v[32:35], v[150:153], v[118:121], v[32:35]
	v_mfma_f32_16x16x32_bf16 v[8:11], v[158:161], v[118:121], v[8:11]
	v_mfma_f32_16x16x32_bf16 v[28:31], v[150:153], v[126:129], v[28:31]
	v_mfma_f32_16x16x32_bf16 v[4:7], v[158:161], v[126:129], v[4:7]
	v_mfma_f32_16x16x32_bf16 v[24:27], v[150:153], v[134:137], v[24:27]
	v_mfma_f32_16x16x32_bf16 v[0:3], v[158:161], v[134:137], v[0:3]
	s_setprio 0
	s_add_i32 s42, 0, 0x18000
	v_add_u32_e32 v96, s42, v229
	s_barrier
	ds_read_b128 v[98:101], v96
	ds_read_b128 v[102:105], v96 offset:1024
	ds_read_b128 v[106:109], v96 offset:2048
	ds_read_b128 v[110:113], v96 offset:3072
	s_add_u32 s30, s46, 0x84000
	s_addc_u32 s31, s47, 0
	s_mov_b32 m0, s96
	v_lshl_add_u64 v[138:139], s[30:31], 0, v[144:145]
	ds_read_b128 v[114:117], v230 offset:32768
	ds_read_b128 v[118:121], v230 offset:33792
	ds_read_b128 v[122:125], v230 offset:34816
	ds_read_b128 v[126:129], v230 offset:35840
	ds_read_b128 v[130:133], v230 offset:36864
	ds_read_b128 v[134:137], v230 offset:37888
	global_load_lds_dwordx4 v[138:139], off
	v_lshl_add_u64 v[138:139], s[30:31], 0, v[142:143]
	s_mov_b32 m0, s97
	s_nop 0
	global_load_lds_dwordx4 v[138:139], off
	s_waitcnt lgkmcnt(6)
	s_barrier
	s_waitcnt lgkmcnt(0)
	s_setprio 1
	s_waitcnt lgkmcnt(0)
	v_mfma_f32_16x16x32_bf16 v[92:95], v[98:101], v[114:117], v[92:95]
	v_mfma_f32_16x16x32_bf16 v[68:71], v[106:109], v[114:117], v[68:71]
	v_mfma_f32_16x16x32_bf16 v[88:91], v[98:101], v[122:125], v[88:91]
	v_mfma_f32_16x16x32_bf16 v[64:67], v[106:109], v[122:125], v[64:67]
	v_mfma_f32_16x16x32_bf16 v[84:87], v[98:101], v[130:133], v[84:87]
	v_mfma_f32_16x16x32_bf16 v[60:63], v[106:109], v[130:133], v[60:63]
	v_mfma_f32_16x16x32_bf16 v[92:95], v[102:105], v[118:121], v[92:95]
	v_mfma_f32_16x16x32_bf16 v[68:71], v[110:113], v[118:121], v[68:71]
	v_mfma_f32_16x16x32_bf16 v[88:91], v[102:105], v[126:129], v[88:91]
	v_mfma_f32_16x16x32_bf16 v[64:67], v[110:113], v[126:129], v[64:67]
	v_mfma_f32_16x16x32_bf16 v[84:87], v[102:105], v[134:137], v[84:87]
	v_mfma_f32_16x16x32_bf16 v[60:63], v[110:113], v[134:137], v[60:63]
	s_setprio 0
	s_barrier
	s_add_i32 s43, 0, 0x1c000
	s_add_i32 s30, s42, s37
	v_add_u32_e32 v96, s43, v229
	v_lshl_add_u64 v[162:163], v[162:163], 0, s[56:57]
	s_mov_b32 m0, s30
	ds_read_b128 v[138:141], v96
	ds_read_b128 v[150:153], v96 offset:1024
	ds_read_b128 v[154:157], v96 offset:2048
	ds_read_b128 v[158:161], v96 offset:3072
	global_load_lds_dwordx4 v[162:163], off
	v_lshl_add_u64 v[162:163], v[164:165], 0, s[56:57]
	s_add_i32 m0, s30, 0x2000
	s_nop 0
	global_load_lds_dwordx4 v[162:163], off
	s_barrier
	s_waitcnt lgkmcnt(0)
	s_setprio 1
	s_waitcnt lgkmcnt(0)
	v_mfma_f32_16x16x32_bf16 v[48:51], v[138:141], v[114:117], v[48:51]
	v_mfma_f32_16x16x32_bf16 v[20:23], v[154:157], v[114:117], v[20:23]
	v_mfma_f32_16x16x32_bf16 v[40:43], v[138:141], v[122:125], v[40:43]
	v_mfma_f32_16x16x32_bf16 v[16:19], v[154:157], v[122:125], v[16:19]
	v_mfma_f32_16x16x32_bf16 v[36:39], v[138:141], v[130:133], v[36:39]
	v_mfma_f32_16x16x32_bf16 v[12:15], v[154:157], v[130:133], v[12:15]
	v_mfma_f32_16x16x32_bf16 v[48:51], v[150:153], v[118:121], v[48:51]
	v_mfma_f32_16x16x32_bf16 v[20:23], v[158:161], v[118:121], v[20:23]
	v_mfma_f32_16x16x32_bf16 v[40:43], v[150:153], v[126:129], v[40:43]
	v_mfma_f32_16x16x32_bf16 v[16:19], v[158:161], v[126:129], v[16:19]
	v_mfma_f32_16x16x32_bf16 v[36:39], v[150:153], v[134:137], v[36:39]
	v_mfma_f32_16x16x32_bf16 v[12:15], v[158:161], v[134:137], v[12:15]
	s_setprio 0
	s_mov_b32 m0, s24
	v_lshl_add_u64 v[162:163], v[166:167], 0, s[56:57]
	s_barrier
	ds_read_b128 v[114:117], v230 offset:49152
	ds_read_b128 v[118:121], v230 offset:50176
	ds_read_b128 v[122:125], v230 offset:51200
	ds_read_b128 v[126:129], v230 offset:52224
	ds_read_b128 v[130:133], v230 offset:53248
	ds_read_b128 v[134:137], v230 offset:54272
	global_load_lds_dwordx4 v[162:163], off
	v_lshl_add_u64 v[162:163], v[168:169], 0, s[56:57]
	s_mov_b32 m0, s36
	s_nop 0
	global_load_lds_dwordx4 v[162:163], off
	s_barrier
	s_waitcnt lgkmcnt(0)
	s_setprio 1
	s_waitcnt lgkmcnt(0)
	v_mfma_f32_16x16x32_bf16 v[80:83], v[98:101], v[114:117], v[80:83]
	v_mfma_f32_16x16x32_bf16 v[56:59], v[106:109], v[114:117], v[56:59]
	v_mfma_f32_16x16x32_bf16 v[76:79], v[98:101], v[122:125], v[76:79]
	v_mfma_f32_16x16x32_bf16 v[52:55], v[106:109], v[122:125], v[52:55]
	v_mfma_f32_16x16x32_bf16 v[72:75], v[98:101], v[130:133], v[72:75]
	v_mfma_f32_16x16x32_bf16 v[44:47], v[106:109], v[130:133], v[44:47]
	v_mfma_f32_16x16x32_bf16 v[80:83], v[102:105], v[118:121], v[80:83]
	v_mfma_f32_16x16x32_bf16 v[56:59], v[110:113], v[118:121], v[56:59]
	v_mfma_f32_16x16x32_bf16 v[76:79], v[102:105], v[126:129], v[76:79]
	v_mfma_f32_16x16x32_bf16 v[52:55], v[110:113], v[126:129], v[52:55]
	v_mfma_f32_16x16x32_bf16 v[72:75], v[102:105], v[134:137], v[72:75]
	v_mfma_f32_16x16x32_bf16 v[44:47], v[110:113], v[134:137], v[44:47]
	s_setprio 0
	s_barrier
	s_add_u32 s30, s44, 0xb0080
	s_addc_u32 s31, s45, 0
	s_add_i32 s42, s43, s37
	v_lshl_add_u64 v[98:99], s[30:31], 0, v[144:145]
	s_mov_b32 m0, s42
	s_nop 0
	global_load_lds_dwordx4 v[98:99], off
	v_lshl_add_u64 v[98:99], s[30:31], 0, v[142:143]
	s_add_i32 m0, s42, 0x2000
	s_nop 0
	global_load_lds_dwordx4 v[98:99], off
	s_waitcnt vmcnt(6)
	s_barrier
	s_setprio 1
	v_mfma_f32_16x16x32_bf16 v[32:35], v[138:141], v[114:117], v[32:35]
	v_mfma_f32_16x16x32_bf16 v[8:11], v[154:157], v[114:117], v[8:11]
	v_mfma_f32_16x16x32_bf16 v[28:31], v[138:141], v[122:125], v[28:31]
	v_mfma_f32_16x16x32_bf16 v[4:7], v[154:157], v[122:125], v[4:7]
	v_mfma_f32_16x16x32_bf16 v[24:27], v[138:141], v[130:133], v[24:27]
	v_mfma_f32_16x16x32_bf16 v[0:3], v[154:157], v[130:133], v[0:3]
	v_mfma_f32_16x16x32_bf16 v[32:35], v[150:153], v[118:121], v[32:35]
	v_mfma_f32_16x16x32_bf16 v[8:11], v[158:161], v[118:121], v[8:11]
	v_mfma_f32_16x16x32_bf16 v[28:31], v[150:153], v[126:129], v[28:31]
	v_mfma_f32_16x16x32_bf16 v[4:7], v[158:161], v[126:129], v[4:7]
	v_mfma_f32_16x16x32_bf16 v[24:27], v[150:153], v[134:137], v[24:27]
	v_mfma_f32_16x16x32_bf16 v[0:3], v[158:161], v[134:137], v[0:3]
	s_setprio 0
	s_add_i32 s52, s52, 2
	s_add_u32 s50, s50, 0x100
	s_addc_u32 s51, s51, 0
	s_cmp_gt_u32 s52, 41
	s_mov_b64 s[30:31], s[0:1]
	s_barrier

.LBB0_73:
	s_ashr_i32 s45, s44, 31
	v_mov_b64_e32 v[0:1], 0x840
	s_lshl_b64 s[42:43], s[44:45], 19
	v_cmp_lt_i64_e32 vcc, s[46:47], v[0:1]
	s_add_u32 s46, s22, s42
	s_addc_u32 s47, s23, s43
	s_and_b64 s[42:43], vcc, exec
	s_cselect_b32 s45, s47, s31
	s_cselect_b32 s75, s46, s30
	s_ashr_i32 s1, s0, 31
	s_lshl_b64 s[42:43], s[0:1], 19
	s_add_u32 s48, s24, s42
	s_addc_u32 s49, s36, s43
	s_and_b64 s[42:43], vcc, exec
	s_cselect_b32 s1, s49, s51
	s_cselect_b32 s76, s48, s50
	s_add_u32 s30, s30, 0x40080
	s_addc_u32 s31, s31, 0
	s_add_u32 s77, s50, 0x100
	s_addc_u32 s78, s51, 0
	s_mov_b32 s79, -2
	s_add_u32 s42, s30, 0xfffc0080
	s_addc_u32 s43, s31, -1
	s_add_i32 s80, 0, 0x10000
	v_add_u32_e32 v140, s80, v144
	ds_read_b128 v[146:149], v140
	ds_read_b128 v[150:153], v140 offset:1024
	ds_read_b128 v[154:157], v140 offset:2048
	ds_read_b128 v[158:161], v140 offset:3072
	s_cmp_eq_u32 s79, 12
	s_cselect_b32 s53, s45, s43
	s_cselect_b32 s52, s75, s42
	s_cselect_b32 s51, s1, s78
	s_cselect_b32 s50, s76, s77
	v_lshl_add_u64 v[140:141], s[30:31], 0, v[136:137]
	s_add_i32 m0, s58, 0xc000
	ds_read_b128 v[166:169], v145
	ds_read_b128 v[174:177], v145 offset:1024
	ds_read_b128 v[178:181], v145 offset:2048
	ds_read_b128 v[182:185], v145 offset:3072
	ds_read_b128 v[186:189], v145 offset:4096
	ds_read_b128 v[190:193], v145 offset:5120
	ds_read_b128 v[194:197], v145 offset:6144
	ds_read_b128 v[198:201], v145 offset:7168
	global_load_lds_dwordx4 v[140:141], off
	v_lshl_add_u64 v[140:141], s[30:31], 0, v[138:139]
	s_add_i32 m0, s58, 0xe000
	s_nop 0
	global_load_lds_dwordx4 v[140:141], off
	s_waitcnt lgkmcnt(8)
	s_barrier
	s_waitcnt lgkmcnt(0)
	s_setprio 1
	s_waitcnt lgkmcnt(0)
	v_mfma_f32_16x16x32_bf16 v[126:129], v[146:149], v[166:169], 0
	v_mfma_f32_16x16x32_bf16 v[114:117], v[154:157], v[166:169], 0
	v_mfma_f32_16x16x32_bf16 v[110:113], v[146:149], v[178:181], 0
	v_mfma_f32_16x16x32_bf16 v[98:101], v[154:157], v[178:181], 0
	v_mfma_f32_16x16x32_bf16 v[92:95], v[146:149], v[186:189], 0
	v_mfma_f32_16x16x32_bf16 v[80:83], v[154:157], v[186:189], 0
	v_mfma_f32_16x16x32_bf16 v[76:79], v[146:149], v[194:197], 0
	v_mfma_f32_16x16x32_bf16 v[64:67], v[154:157], v[194:197], 0
	v_mfma_f32_16x16x32_bf16 v[126:129], v[150:153], v[174:177], v[126:129]
	v_mfma_f32_16x16x32_bf16 v[114:117], v[158:161], v[174:177], v[114:117]
	v_mfma_f32_16x16x32_bf16 v[110:113], v[150:153], v[182:185], v[110:113]
	v_mfma_f32_16x16x32_bf16 v[98:101], v[158:161], v[182:185], v[98:101]
	v_mfma_f32_16x16x32_bf16 v[92:95], v[150:153], v[190:193], v[92:95]
	v_mfma_f32_16x16x32_bf16 v[80:83], v[158:161], v[190:193], v[80:83]
	v_mfma_f32_16x16x32_bf16 v[76:79], v[150:153], v[198:201], v[76:79]
	v_mfma_f32_16x16x32_bf16 v[64:67], v[158:161], v[198:201], v[64:67]
	s_setprio 0
	s_barrier
	s_add_i32 s81, 0, 0x14000
	v_add_u32_e32 v140, s81, v144
	s_add_i32 s42, s80, s37
	ds_read_b128 v[206:209], v140
	ds_read_b128 v[216:219], v140 offset:1024
	ds_read_b128 v[220:223], v140 offset:2048
	ds_read_b128 v[224:227], v140 offset:3072
	v_lshl_add_u64 v[140:141], s[50:51], 0, v[96:97]
	s_mov_b32 m0, s42
	v_lshl_add_u64 v[162:163], s[50:51], 0, v[130:131]
	global_load_lds_dwordx4 v[140:141], off
	s_add_i32 m0, s42, 0x2000
	s_nop 0
	global_load_lds_dwordx4 v[162:163], off
	s_barrier
	s_waitcnt lgkmcnt(0)
	s_setprio 1
	s_waitcnt lgkmcnt(0)
	v_mfma_f32_16x16x32_bf16 v[122:125], v[206:209], v[166:169], 0
	v_mfma_f32_16x16x32_bf16 v[118:121], v[220:223], v[166:169], 0
	v_mfma_f32_16x16x32_bf16 v[106:109], v[206:209], v[178:181], 0
	v_mfma_f32_16x16x32_bf16 v[102:105], v[220:223], v[178:181], 0
	v_mfma_f32_16x16x32_bf16 v[88:91], v[206:209], v[186:189], 0
	v_mfma_f32_16x16x32_bf16 v[84:87], v[220:223], v[186:189], 0
	v_mfma_f32_16x16x32_bf16 v[72:75], v[206:209], v[194:197], 0
	v_mfma_f32_16x16x32_bf16 v[68:71], v[220:223], v[194:197], 0
	v_mfma_f32_16x16x32_bf16 v[122:125], v[216:219], v[174:177], v[122:125]
	v_mfma_f32_16x16x32_bf16 v[118:121], v[224:227], v[174:177], v[118:121]
	v_mfma_f32_16x16x32_bf16 v[106:109], v[216:219], v[182:185], v[106:109]
	v_mfma_f32_16x16x32_bf16 v[102:105], v[224:227], v[182:185], v[102:105]
	v_mfma_f32_16x16x32_bf16 v[88:91], v[216:219], v[190:193], v[88:91]
	v_mfma_f32_16x16x32_bf16 v[84:87], v[224:227], v[190:193], v[84:87]
	v_mfma_f32_16x16x32_bf16 v[72:75], v[216:219], v[198:201], v[72:75]
	v_mfma_f32_16x16x32_bf16 v[68:71], v[224:227], v[198:201], v[68:71]
	s_setprio 0
	s_mov_b32 m0, s58
	v_lshl_add_u64 v[164:165], s[52:53], 0, v[134:135]
	s_barrier
	ds_read_b128 v[166:169], v145 offset:16384
	ds_read_b128 v[174:177], v145 offset:17408
	ds_read_b128 v[178:181], v145 offset:18432
	ds_read_b128 v[182:185], v145 offset:19456
	ds_read_b128 v[186:189], v145 offset:20480
	ds_read_b128 v[190:193], v145 offset:21504
	ds_read_b128 v[194:197], v145 offset:22528
	ds_read_b128 v[198:201], v145 offset:23552
	global_load_lds_dwordx4 v[164:165], off
	v_lshl_add_u64 v[172:173], s[52:53], 0, v[132:133]
	s_mov_b32 m0, s59
	s_nop 0
	global_load_lds_dwordx4 v[172:173], off
	s_barrier
	s_waitcnt lgkmcnt(0)
	s_setprio 1
	s_waitcnt lgkmcnt(0)
	v_mfma_f32_16x16x32_bf16 v[60:63], v[146:149], v[166:169], 0
	v_mfma_f32_16x16x32_bf16 v[48:51], v[154:157], v[166:169], 0
	v_mfma_f32_16x16x32_bf16 v[44:47], v[146:149], v[178:181], 0
	v_mfma_f32_16x16x32_bf16 v[32:35], v[154:157], v[178:181], 0
	v_mfma_f32_16x16x32_bf16 v[28:31], v[146:149], v[186:189], 0
	v_mfma_f32_16x16x32_bf16 v[16:19], v[154:157], v[186:189], 0
	v_mfma_f32_16x16x32_bf16 v[12:15], v[146:149], v[194:197], 0
	v_mfma_f32_16x16x32_bf16 v[4:7], v[154:157], v[194:197], 0
	v_mfma_f32_16x16x32_bf16 v[60:63], v[150:153], v[174:177], v[60:63]
	v_mfma_f32_16x16x32_bf16 v[48:51], v[158:161], v[174:177], v[48:51]
	v_mfma_f32_16x16x32_bf16 v[44:47], v[150:153], v[182:185], v[44:47]
	v_mfma_f32_16x16x32_bf16 v[32:35], v[158:161], v[182:185], v[32:35]
	v_mfma_f32_16x16x32_bf16 v[28:31], v[150:153], v[190:193], v[28:31]
	v_mfma_f32_16x16x32_bf16 v[16:19], v[158:161], v[190:193], v[16:19]
	v_mfma_f32_16x16x32_bf16 v[12:15], v[150:153], v[198:201], v[12:15]
	v_mfma_f32_16x16x32_bf16 v[4:7], v[158:161], v[198:201], v[4:7]
	s_setprio 0
	s_barrier
	s_add_u32 s42, s50, 0x40000
	s_addc_u32 s43, s51, 0
	s_add_i32 s80, s81, s37
	v_lshl_add_u64 v[146:147], s[42:43], 0, v[96:97]
	s_mov_b32 m0, s80
	s_nop 0
	global_load_lds_dwordx4 v[146:147], off
	v_lshl_add_u64 v[146:147], s[42:43], 0, v[130:131]
	s_add_i32 m0, s80, 0x2000
	s_nop 0
	global_load_lds_dwordx4 v[146:147], off
	s_waitcnt vmcnt(6)
	s_barrier
	s_setprio 1
	v_mfma_f32_16x16x32_bf16 v[56:59], v[206:209], v[166:169], 0
	v_mfma_f32_16x16x32_bf16 v[52:55], v[220:223], v[166:169], 0
	v_mfma_f32_16x16x32_bf16 v[40:43], v[206:209], v[178:181], 0
	v_mfma_f32_16x16x32_bf16 v[36:39], v[220:223], v[178:181], 0
	v_mfma_f32_16x16x32_bf16 v[24:27], v[206:209], v[186:189], 0
	v_mfma_f32_16x16x32_bf16 v[20:23], v[220:223], v[186:189], 0
	v_mfma_f32_16x16x32_bf16 v[8:11], v[206:209], v[194:197], 0
	v_mfma_f32_16x16x32_bf16 v[0:3], v[220:223], v[194:197], 0
	v_mfma_f32_16x16x32_bf16 v[56:59], v[216:219], v[174:177], v[56:59]
	v_mfma_f32_16x16x32_bf16 v[52:55], v[224:227], v[174:177], v[52:55]
	v_mfma_f32_16x16x32_bf16 v[40:43], v[216:219], v[182:185], v[40:43]
	v_mfma_f32_16x16x32_bf16 v[36:39], v[224:227], v[182:185], v[36:39]
	v_mfma_f32_16x16x32_bf16 v[24:27], v[216:219], v[190:193], v[24:27]
	v_mfma_f32_16x16x32_bf16 v[20:23], v[224:227], v[190:193], v[20:23]
	v_mfma_f32_16x16x32_bf16 v[8:11], v[216:219], v[198:201], v[8:11]
	v_mfma_f32_16x16x32_bf16 v[0:3], v[224:227], v[198:201], v[0:3]
	s_setprio 0
	s_add_i32 s80, 0, 0x18000
	v_add_u32_e32 v158, s80, v144
	s_barrier
	ds_read_b128 v[146:149], v158
	ds_read_b128 v[150:153], v158 offset:1024
	ds_read_b128 v[154:157], v158 offset:2048
	ds_read_b128 v[158:161], v158 offset:3072
	s_add_u32 s42, s52, 0x40000
	s_addc_u32 s43, s53, 0
	s_mov_b32 m0, s60
	v_lshl_add_u64 v[202:203], s[42:43], 0, v[134:135]
	ds_read_b128 v[166:169], v145 offset:32768
	ds_read_b128 v[174:177], v145 offset:33792
	ds_read_b128 v[178:181], v145 offset:34816
	ds_read_b128 v[182:185], v145 offset:35840
	ds_read_b128 v[186:189], v145 offset:36864
	ds_read_b128 v[190:193], v145 offset:37888
	ds_read_b128 v[194:197], v145 offset:38912
	ds_read_b128 v[198:201], v145 offset:39936
	global_load_lds_dwordx4 v[202:203], off
	v_lshl_add_u64 v[202:203], s[42:43], 0, v[132:133]
	s_mov_b32 m0, s61
	s_nop 0
	global_load_lds_dwordx4 v[202:203], off
	s_waitcnt lgkmcnt(8)
	s_barrier
	s_waitcnt lgkmcnt(0)
	s_setprio 1
	s_waitcnt lgkmcnt(0)
	v_mfma_f32_16x16x32_bf16 v[126:129], v[146:149], v[166:169], v[126:129]
	v_mfma_f32_16x16x32_bf16 v[114:117], v[154:157], v[166:169], v[114:117]
	v_mfma_f32_16x16x32_bf16 v[110:113], v[146:149], v[178:181], v[110:113]
	v_mfma_f32_16x16x32_bf16 v[98:101], v[154:157], v[178:181], v[98:101]
	v_mfma_f32_16x16x32_bf16 v[92:95], v[146:149], v[186:189], v[92:95]
	v_mfma_f32_16x16x32_bf16 v[80:83], v[154:157], v[186:189], v[80:83]
	v_mfma_f32_16x16x32_bf16 v[76:79], v[146:149], v[194:197], v[76:79]
	v_mfma_f32_16x16x32_bf16 v[64:67], v[154:157], v[194:197], v[64:67]
	v_mfma_f32_16x16x32_bf16 v[126:129], v[150:153], v[174:177], v[126:129]
	v_mfma_f32_16x16x32_bf16 v[114:117], v[158:161], v[174:177], v[114:117]
	v_mfma_f32_16x16x32_bf16 v[110:113], v[150:153], v[182:185], v[110:113]
	v_mfma_f32_16x16x32_bf16 v[98:101], v[158:161], v[182:185], v[98:101]
	v_mfma_f32_16x16x32_bf16 v[92:95], v[150:153], v[190:193], v[92:95]
	v_mfma_f32_16x16x32_bf16 v[80:83], v[158:161], v[190:193], v[80:83]
	v_mfma_f32_16x16x32_bf16 v[76:79], v[150:153], v[198:201], v[76:79]
	v_mfma_f32_16x16x32_bf16 v[64:67], v[158:161], v[198:201], v[64:67]
	s_setprio 0
	s_barrier
	s_add_i32 s52, 0, 0x1c000
	s_add_i32 s42, s80, s37
	v_add_u32_e32 v171, s52, v144
	v_lshl_add_u64 v[140:141], v[140:141], 0, s[56:57]
	s_mov_b32 m0, s42
	ds_read_b128 v[206:209], v171
	ds_read_b128 v[216:219], v171 offset:1024
	ds_read_b128 v[220:223], v171 offset:2048
	ds_read_b128 v[224:227], v171 offset:3072
	global_load_lds_dwordx4 v[140:141], off
	v_lshl_add_u64 v[140:141], v[162:163], 0, s[56:57]
	s_add_i32 m0, s42, 0x2000
	s_nop 0
	global_load_lds_dwordx4 v[140:141], off
	s_barrier
	s_waitcnt lgkmcnt(0)
	s_setprio 1
	s_waitcnt lgkmcnt(0)
	v_mfma_f32_16x16x32_bf16 v[122:125], v[206:209], v[166:169], v[122:125]
	v_mfma_f32_16x16x32_bf16 v[118:121], v[220:223], v[166:169], v[118:121]
	v_mfma_f32_16x16x32_bf16 v[106:109], v[206:209], v[178:181], v[106:109]
	v_mfma_f32_16x16x32_bf16 v[102:105], v[220:223], v[178:181], v[102:105]
	v_mfma_f32_16x16x32_bf16 v[88:91], v[206:209], v[186:189], v[88:91]
	v_mfma_f32_16x16x32_bf16 v[84:87], v[220:223], v[186:189], v[84:87]
	v_mfma_f32_16x16x32_bf16 v[72:75], v[206:209], v[194:197], v[72:75]
	v_mfma_f32_16x16x32_bf16 v[68:71], v[220:223], v[194:197], v[68:71]
	v_mfma_f32_16x16x32_bf16 v[122:125], v[216:219], v[174:177], v[122:125]
	v_mfma_f32_16x16x32_bf16 v[118:121], v[224:227], v[174:177], v[118:121]
	v_mfma_f32_16x16x32_bf16 v[106:109], v[216:219], v[182:185], v[106:109]
	v_mfma_f32_16x16x32_bf16 v[102:105], v[224:227], v[182:185], v[102:105]
	v_mfma_f32_16x16x32_bf16 v[88:91], v[216:219], v[190:193], v[88:91]
	v_mfma_f32_16x16x32_bf16 v[84:87], v[224:227], v[190:193], v[84:87]
	v_mfma_f32_16x16x32_bf16 v[72:75], v[216:219], v[198:201], v[72:75]
	v_mfma_f32_16x16x32_bf16 v[68:71], v[224:227], v[198:201], v[68:71]
	s_setprio 0
	s_mov_b32 m0, s70
	v_lshl_add_u64 v[140:141], v[164:165], 0, s[56:57]
	s_barrier
	ds_read_b128 v[166:169], v145 offset:49152
	ds_read_b128 v[174:177], v145 offset:50176
	ds_read_b128 v[178:181], v145 offset:51200
	ds_read_b128 v[182:185], v145 offset:52224
	ds_read_b128 v[186:189], v145 offset:53248
	ds_read_b128 v[190:193], v145 offset:54272
	ds_read_b128 v[194:197], v145 offset:55296
	ds_read_b128 v[198:201], v145 offset:56320
	global_load_lds_dwordx4 v[140:141], off
	v_lshl_add_u64 v[140:141], v[172:173], 0, s[56:57]
	s_mov_b32 m0, s71
	s_nop 0
	global_load_lds_dwordx4 v[140:141], off
	s_barrier
	s_waitcnt lgkmcnt(0)
	s_setprio 1
	s_waitcnt lgkmcnt(0)
	v_mfma_f32_16x16x32_bf16 v[60:63], v[146:149], v[166:169], v[60:63]
	v_mfma_f32_16x16x32_bf16 v[48:51], v[154:157], v[166:169], v[48:51]
	v_mfma_f32_16x16x32_bf16 v[44:47], v[146:149], v[178:181], v[44:47]
	v_mfma_f32_16x16x32_bf16 v[32:35], v[154:157], v[178:181], v[32:35]
	v_mfma_f32_16x16x32_bf16 v[28:31], v[146:149], v[186:189], v[28:31]
	v_mfma_f32_16x16x32_bf16 v[16:19], v[154:157], v[186:189], v[16:19]
	v_mfma_f32_16x16x32_bf16 v[12:15], v[146:149], v[194:197], v[12:15]
	v_mfma_f32_16x16x32_bf16 v[4:7], v[154:157], v[194:197], v[4:7]
	v_mfma_f32_16x16x32_bf16 v[60:63], v[150:153], v[174:177], v[60:63]
	v_mfma_f32_16x16x32_bf16 v[48:51], v[158:161], v[174:177], v[48:51]
	v_mfma_f32_16x16x32_bf16 v[44:47], v[150:153], v[182:185], v[44:47]
	v_mfma_f32_16x16x32_bf16 v[32:35], v[158:161], v[182:185], v[32:35]
	v_mfma_f32_16x16x32_bf16 v[28:31], v[150:153], v[190:193], v[28:31]
	v_mfma_f32_16x16x32_bf16 v[16:19], v[158:161], v[190:193], v[16:19]
	v_mfma_f32_16x16x32_bf16 v[12:15], v[150:153], v[198:201], v[12:15]
	v_mfma_f32_16x16x32_bf16 v[4:7], v[158:161], v[198:201], v[4:7]
	s_setprio 0
	s_barrier
	s_add_u32 s42, s50, 0x40080
	s_addc_u32 s43, s51, 0
	s_add_i32 s50, s52, s37
	v_lshl_add_u64 v[140:141], s[42:43], 0, v[96:97]
	s_mov_b32 m0, s50
	s_nop 0
	global_load_lds_dwordx4 v[140:141], off
	v_lshl_add_u64 v[140:141], s[42:43], 0, v[130:131]
	s_add_i32 m0, s50, 0x2000
	s_nop 0
	global_load_lds_dwordx4 v[140:141], off
	s_waitcnt vmcnt(6)
	s_barrier
	s_setprio 1
	v_mfma_f32_16x16x32_bf16 v[56:59], v[206:209], v[166:169], v[56:59]
	v_mfma_f32_16x16x32_bf16 v[52:55], v[220:223], v[166:169], v[52:55]
	v_mfma_f32_16x16x32_bf16 v[40:43], v[206:209], v[178:181], v[40:43]
	v_mfma_f32_16x16x32_bf16 v[36:39], v[220:223], v[178:181], v[36:39]
	v_mfma_f32_16x16x32_bf16 v[24:27], v[206:209], v[186:189], v[24:27]
	v_mfma_f32_16x16x32_bf16 v[20:23], v[220:223], v[186:189], v[20:23]
	v_mfma_f32_16x16x32_bf16 v[8:11], v[206:209], v[194:197], v[8:11]
	v_mfma_f32_16x16x32_bf16 v[0:3], v[220:223], v[194:197], v[0:3]
	v_mfma_f32_16x16x32_bf16 v[56:59], v[216:219], v[174:177], v[56:59]
	v_mfma_f32_16x16x32_bf16 v[52:55], v[224:227], v[174:177], v[52:55]
	v_mfma_f32_16x16x32_bf16 v[40:43], v[216:219], v[182:185], v[40:43]
	v_mfma_f32_16x16x32_bf16 v[36:39], v[224:227], v[182:185], v[36:39]
	v_mfma_f32_16x16x32_bf16 v[24:27], v[216:219], v[190:193], v[24:27]
	v_mfma_f32_16x16x32_bf16 v[20:23], v[224:227], v[190:193], v[20:23]
	v_mfma_f32_16x16x32_bf16 v[8:11], v[216:219], v[198:201], v[8:11]
	v_mfma_f32_16x16x32_bf16 v[0:3], v[224:227], v[198:201], v[0:3]
	s_setprio 0
	s_add_i32 s79, s79, 2
	s_add_u32 s30, s30, 0x100
	s_addc_u32 s31, s31, 0
	s_add_u32 s77, s77, 0x100
	s_addc_u32 s78, s78, 0
	s_cmp_gt_u32 s79, 13
	s_barrier

.LBB0_106:
	s_ashr_i32 s61, s60, 31
	s_lshl_b64 s[42:43], s[60:61], 19
	s_add_u32 s70, s24, s42
	s_addc_u32 s71, s36, s43
	s_and_b64 s[0:1], s[0:1], exec
	s_cselect_b32 s50, s71, s45
	s_cselect_b32 s51, s70, s44
	s_add_u32 s52, s44, 0x100
	s_addc_u32 s53, s45, 0
	s_mov_b32 s61, -2
	s_add_u32 s0, s30, 0x100
	s_addc_u32 s1, s31, 0
	s_add_i32 s42, 0, 0x10000
	v_add_u32_e32 v96, s42, v203
	ds_read_b128 v[98:101], v96
	ds_read_b128 v[102:105], v96 offset:1024
	ds_read_b128 v[106:109], v96 offset:2048
	ds_read_b128 v[110:113], v96 offset:3072
	s_cmp_eq_u32 s61, 12
	s_cselect_b32 s47, s69, s1
	s_cselect_b32 s46, s68, s0
	s_cselect_b32 s45, s50, s53
	s_cselect_b32 s44, s51, s52
	v_lshl_add_u64 v[146:147], s[30:31], 0, v[142:143]
	s_add_i32 m0, s72, 0xc000
	ds_read_b128 v[114:117], v228
	ds_read_b128 v[118:121], v228 offset:1024
	ds_read_b128 v[122:125], v228 offset:2048
	ds_read_b128 v[126:129], v228 offset:3072
	ds_read_b128 v[130:133], v228 offset:4096
	ds_read_b128 v[134:137], v228 offset:5120
	global_load_lds_dwordx4 v[146:147], off
	v_lshl_add_u64 v[146:147], s[30:31], 0, v[144:145]
	s_add_i32 m0, s72, 0xe000
	s_nop 0
	global_load_lds_dwordx4 v[146:147], off
	s_waitcnt lgkmcnt(6)
	s_barrier
	s_waitcnt lgkmcnt(0)
	s_setprio 1
	s_waitcnt lgkmcnt(0)
	v_mfma_f32_16x16x32_bf16 v[92:95], v[98:101], v[114:117], 0
	v_mfma_f32_16x16x32_bf16 v[68:71], v[106:109], v[114:117], 0
	v_mfma_f32_16x16x32_bf16 v[88:91], v[98:101], v[122:125], 0
	v_mfma_f32_16x16x32_bf16 v[64:67], v[106:109], v[122:125], 0
	v_mfma_f32_16x16x32_bf16 v[84:87], v[98:101], v[130:133], 0
	v_mfma_f32_16x16x32_bf16 v[60:63], v[106:109], v[130:133], 0
	v_mfma_f32_16x16x32_bf16 v[92:95], v[102:105], v[118:121], v[92:95]
	v_mfma_f32_16x16x32_bf16 v[68:71], v[110:113], v[118:121], v[68:71]
	v_mfma_f32_16x16x32_bf16 v[88:91], v[102:105], v[126:129], v[88:91]
	v_mfma_f32_16x16x32_bf16 v[64:67], v[110:113], v[126:129], v[64:67]
	v_mfma_f32_16x16x32_bf16 v[84:87], v[102:105], v[134:137], v[84:87]
	v_mfma_f32_16x16x32_bf16 v[60:63], v[110:113], v[134:137], v[60:63]
	s_setprio 0
	s_barrier
	s_add_i32 s43, 0, 0x14000
	s_add_i32 s30, s42, s37
	v_add_u32_e32 v96, s43, v203
	v_lshl_add_u64 v[162:163], s[44:45], 0, v[140:141]
	s_mov_b32 m0, s30
	ds_read_b128 v[146:149], v96
	ds_read_b128 v[150:153], v96 offset:1024
	ds_read_b128 v[154:157], v96 offset:2048
	ds_read_b128 v[158:161], v96 offset:3072
	global_load_lds_dwordx4 v[162:163], off
	v_lshl_add_u64 v[164:165], s[44:45], 0, v[138:139]
	s_add_i32 m0, s30, 0x2000
	s_nop 0
	global_load_lds_dwordx4 v[164:165], off
	s_barrier
	s_waitcnt lgkmcnt(0)
	s_setprio 1
	s_waitcnt lgkmcnt(0)
	v_mfma_f32_16x16x32_bf16 v[44:47], v[146:149], v[114:117], 0
	v_mfma_f32_16x16x32_bf16 v[20:23], v[154:157], v[114:117], 0
	v_mfma_f32_16x16x32_bf16 v[40:43], v[146:149], v[122:125], 0
	v_mfma_f32_16x16x32_bf16 v[16:19], v[154:157], v[122:125], 0
	v_mfma_f32_16x16x32_bf16 v[36:39], v[146:149], v[130:133], 0
	v_mfma_f32_16x16x32_bf16 v[12:15], v[154:157], v[130:133], 0
	v_mfma_f32_16x16x32_bf16 v[44:47], v[150:153], v[118:121], v[44:47]
	v_mfma_f32_16x16x32_bf16 v[20:23], v[158:161], v[118:121], v[20:23]
	v_mfma_f32_16x16x32_bf16 v[40:43], v[150:153], v[126:129], v[40:43]
	v_mfma_f32_16x16x32_bf16 v[16:19], v[158:161], v[126:129], v[16:19]
	v_mfma_f32_16x16x32_bf16 v[36:39], v[150:153], v[134:137], v[36:39]
	v_mfma_f32_16x16x32_bf16 v[12:15], v[158:161], v[134:137], v[12:15]
	s_setprio 0
	s_mov_b32 m0, s72
	v_lshl_add_u64 v[166:167], s[46:47], 0, v[140:141]
	s_barrier
	ds_read_b128 v[114:117], v228 offset:16384
	ds_read_b128 v[118:121], v228 offset:17408
	ds_read_b128 v[122:125], v228 offset:18432
	ds_read_b128 v[126:129], v228 offset:19456
	ds_read_b128 v[130:133], v228 offset:20480
	ds_read_b128 v[134:137], v228 offset:21504
	global_load_lds_dwordx4 v[166:167], off
	v_lshl_add_u64 v[168:169], s[46:47], 0, v[138:139]
	s_mov_b32 m0, s73
	s_nop 0
	global_load_lds_dwordx4 v[168:169], off
	s_barrier
	s_waitcnt lgkmcnt(0)
	s_setprio 1
	s_waitcnt lgkmcnt(0)
	v_mfma_f32_16x16x32_bf16 v[80:83], v[98:101], v[114:117], 0
	v_mfma_f32_16x16x32_bf16 v[56:59], v[106:109], v[114:117], 0
	v_mfma_f32_16x16x32_bf16 v[76:79], v[98:101], v[122:125], 0
	v_mfma_f32_16x16x32_bf16 v[52:55], v[106:109], v[122:125], 0
	v_mfma_f32_16x16x32_bf16 v[72:75], v[98:101], v[130:133], 0
	v_mfma_f32_16x16x32_bf16 v[48:51], v[106:109], v[130:133], 0
	v_mfma_f32_16x16x32_bf16 v[80:83], v[102:105], v[118:121], v[80:83]
	v_mfma_f32_16x16x32_bf16 v[56:59], v[110:113], v[118:121], v[56:59]
	v_mfma_f32_16x16x32_bf16 v[76:79], v[102:105], v[126:129], v[76:79]
	v_mfma_f32_16x16x32_bf16 v[52:55], v[110:113], v[126:129], v[52:55]
	v_mfma_f32_16x16x32_bf16 v[72:75], v[102:105], v[134:137], v[72:75]
	v_mfma_f32_16x16x32_bf16 v[48:51], v[110:113], v[134:137], v[48:51]
	s_setprio 0
	s_barrier
	s_add_u32 s30, s44, 0x40000
	s_addc_u32 s31, s45, 0
	s_add_i32 s42, s43, s37
	v_lshl_add_u64 v[98:99], s[30:31], 0, v[140:141]
	s_mov_b32 m0, s42
	s_nop 0
	global_load_lds_dwordx4 v[98:99], off
	v_lshl_add_u64 v[98:99], s[30:31], 0, v[138:139]
	s_add_i32 m0, s42, 0x2000
	s_nop 0
	global_load_lds_dwordx4 v[98:99], off
	s_waitcnt vmcnt(6)
	s_barrier
	s_setprio 1
	v_mfma_f32_16x16x32_bf16 v[32:35], v[146:149], v[114:117], 0
	v_mfma_f32_16x16x32_bf16 v[8:11], v[154:157], v[114:117], 0
	v_mfma_f32_16x16x32_bf16 v[28:31], v[146:149], v[122:125], 0
	v_mfma_f32_16x16x32_bf16 v[4:7], v[154:157], v[122:125], 0
	v_mfma_f32_16x16x32_bf16 v[24:27], v[146:149], v[130:133], 0
	v_mfma_f32_16x16x32_bf16 v[0:3], v[154:157], v[130:133], 0
	v_mfma_f32_16x16x32_bf16 v[32:35], v[150:153], v[118:121], v[32:35]
	v_mfma_f32_16x16x32_bf16 v[8:11], v[158:161], v[118:121], v[8:11]
	v_mfma_f32_16x16x32_bf16 v[28:31], v[150:153], v[126:129], v[28:31]
	v_mfma_f32_16x16x32_bf16 v[4:7], v[158:161], v[126:129], v[4:7]
	v_mfma_f32_16x16x32_bf16 v[24:27], v[150:153], v[134:137], v[24:27]
	v_mfma_f32_16x16x32_bf16 v[0:3], v[158:161], v[134:137], v[0:3]
	s_setprio 0
	s_add_i32 s42, 0, 0x18000
	v_add_u32_e32 v96, s42, v203
	s_barrier
	ds_read_b128 v[98:101], v96
	ds_read_b128 v[102:105], v96 offset:1024
	ds_read_b128 v[106:109], v96 offset:2048
	ds_read_b128 v[110:113], v96 offset:3072
	s_add_u32 s30, s46, 0x30000
	s_addc_u32 s31, s47, 0
	s_mov_b32 m0, s74
	v_lshl_add_u64 v[146:147], s[30:31], 0, v[140:141]
	ds_read_b128 v[114:117], v228 offset:32768
	ds_read_b128 v[118:121], v228 offset:33792
	ds_read_b128 v[122:125], v228 offset:34816
	ds_read_b128 v[126:129], v228 offset:35840
	ds_read_b128 v[130:133], v228 offset:36864
	ds_read_b128 v[134:137], v228 offset:37888
	global_load_lds_dwordx4 v[146:147], off
	v_lshl_add_u64 v[146:147], s[30:31], 0, v[138:139]
	s_mov_b32 m0, s75
	s_nop 0
	global_load_lds_dwordx4 v[146:147], off
	s_waitcnt lgkmcnt(6)
	s_barrier
	s_waitcnt lgkmcnt(0)
	s_setprio 1
	s_waitcnt lgkmcnt(0)
	v_mfma_f32_16x16x32_bf16 v[92:95], v[98:101], v[114:117], v[92:95]
	v_mfma_f32_16x16x32_bf16 v[68:71], v[106:109], v[114:117], v[68:71]
	v_mfma_f32_16x16x32_bf16 v[88:91], v[98:101], v[122:125], v[88:91]
	v_mfma_f32_16x16x32_bf16 v[64:67], v[106:109], v[122:125], v[64:67]
	v_mfma_f32_16x16x32_bf16 v[84:87], v[98:101], v[130:133], v[84:87]
	v_mfma_f32_16x16x32_bf16 v[60:63], v[106:109], v[130:133], v[60:63]
	v_mfma_f32_16x16x32_bf16 v[92:95], v[102:105], v[118:121], v[92:95]
	v_mfma_f32_16x16x32_bf16 v[68:71], v[110:113], v[118:121], v[68:71]
	v_mfma_f32_16x16x32_bf16 v[88:91], v[102:105], v[126:129], v[88:91]
	v_mfma_f32_16x16x32_bf16 v[64:67], v[110:113], v[126:129], v[64:67]
	v_mfma_f32_16x16x32_bf16 v[84:87], v[102:105], v[134:137], v[84:87]
	v_mfma_f32_16x16x32_bf16 v[60:63], v[110:113], v[134:137], v[60:63]
	s_setprio 0
	s_barrier
	s_add_i32 s43, 0, 0x1c000
	s_add_i32 s30, s42, s37
	v_add_u32_e32 v96, s43, v203
	v_lshl_add_u64 v[162:163], v[162:163], 0, s[56:57]
	s_mov_b32 m0, s30
	ds_read_b128 v[146:149], v96
	ds_read_b128 v[150:153], v96 offset:1024
	ds_read_b128 v[154:157], v96 offset:2048
	ds_read_b128 v[158:161], v96 offset:3072
	global_load_lds_dwordx4 v[162:163], off
	v_lshl_add_u64 v[162:163], v[164:165], 0, s[56:57]
	s_add_i32 m0, s30, 0x2000
	s_nop 0
	global_load_lds_dwordx4 v[162:163], off
	s_barrier
	s_waitcnt lgkmcnt(0)
	s_setprio 1
	s_waitcnt lgkmcnt(0)
	v_mfma_f32_16x16x32_bf16 v[44:47], v[146:149], v[114:117], v[44:47]
	v_mfma_f32_16x16x32_bf16 v[20:23], v[154:157], v[114:117], v[20:23]
	v_mfma_f32_16x16x32_bf16 v[40:43], v[146:149], v[122:125], v[40:43]
	v_mfma_f32_16x16x32_bf16 v[16:19], v[154:157], v[122:125], v[16:19]
	v_mfma_f32_16x16x32_bf16 v[36:39], v[146:149], v[130:133], v[36:39]
	v_mfma_f32_16x16x32_bf16 v[12:15], v[154:157], v[130:133], v[12:15]
	v_mfma_f32_16x16x32_bf16 v[44:47], v[150:153], v[118:121], v[44:47]
	v_mfma_f32_16x16x32_bf16 v[20:23], v[158:161], v[118:121], v[20:23]
	v_mfma_f32_16x16x32_bf16 v[40:43], v[150:153], v[126:129], v[40:43]
	v_mfma_f32_16x16x32_bf16 v[16:19], v[158:161], v[126:129], v[16:19]
	v_mfma_f32_16x16x32_bf16 v[36:39], v[150:153], v[134:137], v[36:39]
	v_mfma_f32_16x16x32_bf16 v[12:15], v[158:161], v[134:137], v[12:15]
	s_setprio 0
	s_mov_b32 m0, s77
	v_lshl_add_u64 v[162:163], v[166:167], 0, s[56:57]
	s_barrier
	ds_read_b128 v[114:117], v228 offset:49152
	ds_read_b128 v[118:121], v228 offset:50176
	ds_read_b128 v[122:125], v228 offset:51200
	ds_read_b128 v[126:129], v228 offset:52224
	ds_read_b128 v[130:133], v228 offset:53248
	ds_read_b128 v[134:137], v228 offset:54272
	global_load_lds_dwordx4 v[162:163], off
	v_lshl_add_u64 v[162:163], v[168:169], 0, s[56:57]
	s_mov_b32 m0, s78
	s_nop 0
	global_load_lds_dwordx4 v[162:163], off
	s_barrier
	s_waitcnt lgkmcnt(0)
	s_setprio 1
	s_waitcnt lgkmcnt(0)
	v_mfma_f32_16x16x32_bf16 v[80:83], v[98:101], v[114:117], v[80:83]
	v_mfma_f32_16x16x32_bf16 v[56:59], v[106:109], v[114:117], v[56:59]
	v_mfma_f32_16x16x32_bf16 v[76:79], v[98:101], v[122:125], v[76:79]
	v_mfma_f32_16x16x32_bf16 v[52:55], v[106:109], v[122:125], v[52:55]
	v_mfma_f32_16x16x32_bf16 v[72:75], v[98:101], v[130:133], v[72:75]
	v_mfma_f32_16x16x32_bf16 v[48:51], v[106:109], v[130:133], v[48:51]
	v_mfma_f32_16x16x32_bf16 v[80:83], v[102:105], v[118:121], v[80:83]
	v_mfma_f32_16x16x32_bf16 v[56:59], v[110:113], v[118:121], v[56:59]
	v_mfma_f32_16x16x32_bf16 v[76:79], v[102:105], v[126:129], v[76:79]
	v_mfma_f32_16x16x32_bf16 v[52:55], v[110:113], v[126:129], v[52:55]
	v_mfma_f32_16x16x32_bf16 v[72:75], v[102:105], v[134:137], v[72:75]
	v_mfma_f32_16x16x32_bf16 v[48:51], v[110:113], v[134:137], v[48:51]
	s_setprio 0
	s_barrier
	s_add_u32 s30, s44, 0x40080
	s_addc_u32 s31, s45, 0
	s_add_i32 s42, s43, s37
	v_lshl_add_u64 v[98:99], s[30:31], 0, v[140:141]
	s_mov_b32 m0, s42
	s_nop 0
	global_load_lds_dwordx4 v[98:99], off
	v_lshl_add_u64 v[98:99], s[30:31], 0, v[138:139]
	s_add_i32 m0, s42, 0x2000
	s_nop 0
	global_load_lds_dwordx4 v[98:99], off
	s_waitcnt vmcnt(6)
	s_barrier
	s_setprio 1
	v_mfma_f32_16x16x32_bf16 v[32:35], v[146:149], v[114:117], v[32:35]
	v_mfma_f32_16x16x32_bf16 v[8:11], v[154:157], v[114:117], v[8:11]
	v_mfma_f32_16x16x32_bf16 v[28:31], v[146:149], v[122:125], v[28:31]
	v_mfma_f32_16x16x32_bf16 v[4:7], v[154:157], v[122:125], v[4:7]
	v_mfma_f32_16x16x32_bf16 v[24:27], v[146:149], v[130:133], v[24:27]
	v_mfma_f32_16x16x32_bf16 v[0:3], v[154:157], v[130:133], v[0:3]
	v_mfma_f32_16x16x32_bf16 v[32:35], v[150:153], v[118:121], v[32:35]
	v_mfma_f32_16x16x32_bf16 v[8:11], v[158:161], v[118:121], v[8:11]
	v_mfma_f32_16x16x32_bf16 v[28:31], v[150:153], v[126:129], v[28:31]
	v_mfma_f32_16x16x32_bf16 v[4:7], v[158:161], v[126:129], v[4:7]
	v_mfma_f32_16x16x32_bf16 v[24:27], v[150:153], v[134:137], v[24:27]
	v_mfma_f32_16x16x32_bf16 v[0:3], v[158:161], v[134:137], v[0:3]
	s_setprio 0
	s_add_i32 s61, s61, 2
	s_add_u32 s52, s52, 0x100
	s_addc_u32 s53, s53, 0
	s_cmp_gt_u32 s61, 13
	s_mov_b64 s[30:31], s[0:1]
	s_barrier

.LBB0_425:
	s_ashr_i32 s31, s30, 31
	v_mov_b64_e32 v[0:1], 0x240
	s_lshl_b64 s[42:43], s[30:31], 19
	v_cmp_lt_i64_e32 vcc, s[44:45], v[0:1]
	s_add_u32 s44, s22, s42
	s_addc_u32 s45, s23, s43
	s_and_b64 s[42:43], vcc, exec
	s_cselect_b32 s31, s45, s49
	s_cselect_b32 s73, s44, s48
	s_ashr_i32 s1, s0, 31
	s_lshl_b64 s[42:43], s[0:1], 19
	v_readlane_b32 s1, v252, 10
	s_add_u32 s46, s1, s42
	v_readlane_b32 s1, v252, 11
	s_addc_u32 s47, s1, s43
	s_and_b64 s[42:43], vcc, exec
	s_cselect_b32 s1, s47, s51
	s_cselect_b32 s74, s46, s50
	s_add_u32 s48, s48, 0x40080
	s_addc_u32 s49, s49, 0
	s_add_u32 s75, s50, 0x100
	s_addc_u32 s76, s51, 0
	s_mov_b32 s77, -2
	s_add_u32 s42, s48, 0xfffc0080
	s_addc_u32 s43, s49, -1
	s_add_i32 s78, 0, 0x10000
	v_add_u32_e32 v156, s78, v142
	ds_read_b128 v[144:147], v156
	ds_read_b128 v[148:151], v156 offset:1024
	ds_read_b128 v[152:155], v156 offset:2048
	ds_read_b128 v[156:159], v156 offset:3072
	s_cmp_eq_u32 s77, 12
	s_cselect_b32 s53, s31, s43
	s_cselect_b32 s52, s73, s42
	s_cselect_b32 s51, s1, s76
	s_cselect_b32 s50, s74, s75
	v_lshl_add_u64 v[160:161], s[48:49], 0, v[136:137]
	s_add_i32 m0, s36, 0xc000
	ds_read_b128 v[174:177], v143
	ds_read_b128 v[178:181], v143 offset:1024
	ds_read_b128 v[182:185], v143 offset:2048
	ds_read_b128 v[186:189], v143 offset:3072
	ds_read_b128 v[190:193], v143 offset:4096
	ds_read_b128 v[194:197], v143 offset:5120
	ds_read_b128 v[198:201], v143 offset:6144
	ds_read_b128 v[228:231], v143 offset:7168
	global_load_lds_dwordx4 v[160:161], off
	v_lshl_add_u64 v[160:161], s[48:49], 0, v[138:139]
	s_add_i32 m0, s36, 0xe000
	s_nop 0
	global_load_lds_dwordx4 v[160:161], off
	s_waitcnt lgkmcnt(8)
	s_barrier
	s_waitcnt lgkmcnt(0)
	s_setprio 1
	s_waitcnt lgkmcnt(0)
	v_mfma_f32_16x16x32_bf16 v[126:129], v[144:147], v[174:177], 0
	v_mfma_f32_16x16x32_bf16 v[122:125], v[152:155], v[174:177], 0
	v_mfma_f32_16x16x32_bf16 v[118:121], v[144:147], v[182:185], 0
	v_mfma_f32_16x16x32_bf16 v[114:117], v[152:155], v[182:185], 0
	v_mfma_f32_16x16x32_bf16 v[102:105], v[144:147], v[190:193], 0
	v_mfma_f32_16x16x32_bf16 v[98:101], v[152:155], v[190:193], 0
	v_mfma_f32_16x16x32_bf16 v[84:87], v[144:147], v[198:201], 0
	v_mfma_f32_16x16x32_bf16 v[80:83], v[152:155], v[198:201], 0
	v_mfma_f32_16x16x32_bf16 v[126:129], v[148:151], v[178:181], v[126:129]
	v_mfma_f32_16x16x32_bf16 v[122:125], v[156:159], v[178:181], v[122:125]
	v_mfma_f32_16x16x32_bf16 v[118:121], v[148:151], v[186:189], v[118:121]
	v_mfma_f32_16x16x32_bf16 v[114:117], v[156:159], v[186:189], v[114:117]
	v_mfma_f32_16x16x32_bf16 v[102:105], v[148:151], v[194:197], v[102:105]
	v_mfma_f32_16x16x32_bf16 v[98:101], v[156:159], v[194:197], v[98:101]
	v_mfma_f32_16x16x32_bf16 v[84:87], v[148:151], v[228:231], v[84:87]
	v_mfma_f32_16x16x32_bf16 v[80:83], v[156:159], v[228:231], v[80:83]
	s_setprio 0
	s_barrier
	s_add_i32 s79, 0, 0x14000
	v_add_u32_e32 v160, s79, v142
	s_add_i32 s42, s78, s24
	ds_read_b128 v[232:235], v160
	ds_read_b128 v[236:239], v160 offset:1024
	ds_read_b128 v[240:243], v160 offset:2048
	ds_read_b128 v[244:247], v160 offset:3072
	v_lshl_add_u64 v[160:161], s[50:51], 0, v[96:97]
	s_mov_b32 m0, s42
	v_lshl_add_u64 v[162:163], s[50:51], 0, v[130:131]
	global_load_lds_dwordx4 v[160:161], off
	s_add_i32 m0, s42, 0x2000
	s_nop 0
	global_load_lds_dwordx4 v[162:163], off
	s_barrier
	s_waitcnt lgkmcnt(0)
	s_setprio 1
	s_waitcnt lgkmcnt(0)
	v_mfma_f32_16x16x32_bf16 v[110:113], v[232:235], v[174:177], 0
	v_mfma_f32_16x16x32_bf16 v[106:109], v[240:243], v[174:177], 0
	v_mfma_f32_16x16x32_bf16 v[92:95], v[232:235], v[182:185], 0
	v_mfma_f32_16x16x32_bf16 v[88:91], v[240:243], v[182:185], 0
	v_mfma_f32_16x16x32_bf16 v[76:79], v[232:235], v[190:193], 0
	v_mfma_f32_16x16x32_bf16 v[72:75], v[240:243], v[190:193], 0
	v_mfma_f32_16x16x32_bf16 v[68:71], v[232:235], v[198:201], 0
	v_mfma_f32_16x16x32_bf16 v[64:67], v[240:243], v[198:201], 0
	v_mfma_f32_16x16x32_bf16 v[110:113], v[236:239], v[178:181], v[110:113]
	v_mfma_f32_16x16x32_bf16 v[106:109], v[244:247], v[178:181], v[106:109]
	v_mfma_f32_16x16x32_bf16 v[92:95], v[236:239], v[186:189], v[92:95]
	v_mfma_f32_16x16x32_bf16 v[88:91], v[244:247], v[186:189], v[88:91]
	v_mfma_f32_16x16x32_bf16 v[76:79], v[236:239], v[194:197], v[76:79]
	v_mfma_f32_16x16x32_bf16 v[72:75], v[244:247], v[194:197], v[72:75]
	v_mfma_f32_16x16x32_bf16 v[68:71], v[236:239], v[228:231], v[68:71]
	v_mfma_f32_16x16x32_bf16 v[64:67], v[244:247], v[228:231], v[64:67]
	s_setprio 0
	s_mov_b32 m0, s36
	v_lshl_add_u64 v[166:167], s[52:53], 0, v[134:135]
	s_barrier
	ds_read_b128 v[174:177], v143 offset:16384
	ds_read_b128 v[178:181], v143 offset:17408
	ds_read_b128 v[182:185], v143 offset:18432
	ds_read_b128 v[186:189], v143 offset:19456
	ds_read_b128 v[190:193], v143 offset:20480
	ds_read_b128 v[194:197], v143 offset:21504
	ds_read_b128 v[198:201], v143 offset:22528
	ds_read_b128 v[228:231], v143 offset:23552
	global_load_lds_dwordx4 v[166:167], off
	v_lshl_add_u64 v[168:169], s[52:53], 0, v[132:133]
	s_mov_b32 m0, s37
	s_nop 0
	global_load_lds_dwordx4 v[168:169], off
	s_barrier
	s_waitcnt lgkmcnt(0)
	s_setprio 1
	s_waitcnt lgkmcnt(0)
	v_mfma_f32_16x16x32_bf16 v[60:63], v[144:147], v[174:177], 0
	v_mfma_f32_16x16x32_bf16 v[56:59], v[152:155], v[174:177], 0
	v_mfma_f32_16x16x32_bf16 v[52:55], v[144:147], v[182:185], 0
	v_mfma_f32_16x16x32_bf16 v[48:51], v[152:155], v[182:185], 0
	v_mfma_f32_16x16x32_bf16 v[36:39], v[144:147], v[190:193], 0
	v_mfma_f32_16x16x32_bf16 v[32:35], v[152:155], v[190:193], 0
	v_mfma_f32_16x16x32_bf16 v[20:23], v[144:147], v[198:201], 0
	v_mfma_f32_16x16x32_bf16 v[16:19], v[152:155], v[198:201], 0
	v_mfma_f32_16x16x32_bf16 v[60:63], v[148:151], v[178:181], v[60:63]
	v_mfma_f32_16x16x32_bf16 v[56:59], v[156:159], v[178:181], v[56:59]
	v_mfma_f32_16x16x32_bf16 v[52:55], v[148:151], v[186:189], v[52:55]
	v_mfma_f32_16x16x32_bf16 v[48:51], v[156:159], v[186:189], v[48:51]
	v_mfma_f32_16x16x32_bf16 v[36:39], v[148:151], v[194:197], v[36:39]
	v_mfma_f32_16x16x32_bf16 v[32:35], v[156:159], v[194:197], v[32:35]
	v_mfma_f32_16x16x32_bf16 v[20:23], v[148:151], v[228:231], v[20:23]
	v_mfma_f32_16x16x32_bf16 v[16:19], v[156:159], v[228:231], v[16:19]
	s_setprio 0
	s_barrier
	s_add_u32 s42, s50, 0x40000
	s_addc_u32 s43, s51, 0
	s_add_i32 s78, s79, s24
	v_lshl_add_u64 v[144:145], s[42:43], 0, v[96:97]
	s_mov_b32 m0, s78
	s_nop 0
	global_load_lds_dwordx4 v[144:145], off
	v_lshl_add_u64 v[144:145], s[42:43], 0, v[130:131]
	s_add_i32 m0, s78, 0x2000
	s_nop 0
	global_load_lds_dwordx4 v[144:145], off
	s_waitcnt vmcnt(6)
	s_barrier
	s_setprio 1
	v_mfma_f32_16x16x32_bf16 v[44:47], v[232:235], v[174:177], 0
	v_mfma_f32_16x16x32_bf16 v[40:43], v[240:243], v[174:177], 0
	v_mfma_f32_16x16x32_bf16 v[28:31], v[232:235], v[182:185], 0
	v_mfma_f32_16x16x32_bf16 v[24:27], v[240:243], v[182:185], 0
	v_mfma_f32_16x16x32_bf16 v[12:15], v[232:235], v[190:193], 0
	v_mfma_f32_16x16x32_bf16 v[8:11], v[240:243], v[190:193], 0
	v_mfma_f32_16x16x32_bf16 v[4:7], v[232:235], v[198:201], 0
	v_mfma_f32_16x16x32_bf16 v[0:3], v[240:243], v[198:201], 0
	v_mfma_f32_16x16x32_bf16 v[44:47], v[236:239], v[178:181], v[44:47]
	v_mfma_f32_16x16x32_bf16 v[40:43], v[244:247], v[178:181], v[40:43]
	v_mfma_f32_16x16x32_bf16 v[28:31], v[236:239], v[186:189], v[28:31]
	v_mfma_f32_16x16x32_bf16 v[24:27], v[244:247], v[186:189], v[24:27]
	v_mfma_f32_16x16x32_bf16 v[12:15], v[236:239], v[194:197], v[12:15]
	v_mfma_f32_16x16x32_bf16 v[8:11], v[244:247], v[194:197], v[8:11]
	v_mfma_f32_16x16x32_bf16 v[4:7], v[236:239], v[228:231], v[4:7]
	v_mfma_f32_16x16x32_bf16 v[0:3], v[244:247], v[228:231], v[0:3]
	s_setprio 0
	s_add_i32 s78, 0, 0x18000
	v_add_u32_e32 v156, s78, v142
	s_barrier
	ds_read_b128 v[144:147], v156
	ds_read_b128 v[148:151], v156 offset:1024
	ds_read_b128 v[152:155], v156 offset:2048
	ds_read_b128 v[156:159], v156 offset:3072
	s_add_u32 s42, s52, 0x40000
	s_addc_u32 s43, s53, 0
	s_mov_b32 m0, s58
	v_lshl_add_u64 v[202:203], s[42:43], 0, v[134:135]
	ds_read_b128 v[174:177], v143 offset:32768
	ds_read_b128 v[178:181], v143 offset:33792
	ds_read_b128 v[182:185], v143 offset:34816
	ds_read_b128 v[186:189], v143 offset:35840
	ds_read_b128 v[190:193], v143 offset:36864
	ds_read_b128 v[194:197], v143 offset:37888
	ds_read_b128 v[198:201], v143 offset:38912
	ds_read_b128 v[228:231], v143 offset:39936
	global_load_lds_dwordx4 v[202:203], off
	v_lshl_add_u64 v[202:203], s[42:43], 0, v[132:133]
	s_mov_b32 m0, s59
	s_nop 0
	global_load_lds_dwordx4 v[202:203], off
	s_waitcnt lgkmcnt(8)
	s_barrier
	s_waitcnt lgkmcnt(0)
	s_setprio 1
	s_waitcnt lgkmcnt(0)
	v_mfma_f32_16x16x32_bf16 v[126:129], v[144:147], v[174:177], v[126:129]
	v_mfma_f32_16x16x32_bf16 v[122:125], v[152:155], v[174:177], v[122:125]
	v_mfma_f32_16x16x32_bf16 v[118:121], v[144:147], v[182:185], v[118:121]
	v_mfma_f32_16x16x32_bf16 v[114:117], v[152:155], v[182:185], v[114:117]
	v_mfma_f32_16x16x32_bf16 v[102:105], v[144:147], v[190:193], v[102:105]
	v_mfma_f32_16x16x32_bf16 v[98:101], v[152:155], v[190:193], v[98:101]
	v_mfma_f32_16x16x32_bf16 v[84:87], v[144:147], v[198:201], v[84:87]
	v_mfma_f32_16x16x32_bf16 v[80:83], v[152:155], v[198:201], v[80:83]
	v_mfma_f32_16x16x32_bf16 v[126:129], v[148:151], v[178:181], v[126:129]
	v_mfma_f32_16x16x32_bf16 v[122:125], v[156:159], v[178:181], v[122:125]
	v_mfma_f32_16x16x32_bf16 v[118:121], v[148:151], v[186:189], v[118:121]
	v_mfma_f32_16x16x32_bf16 v[114:117], v[156:159], v[186:189], v[114:117]
	v_mfma_f32_16x16x32_bf16 v[102:105], v[148:151], v[194:197], v[102:105]
	v_mfma_f32_16x16x32_bf16 v[98:101], v[156:159], v[194:197], v[98:101]
	v_mfma_f32_16x16x32_bf16 v[84:87], v[148:151], v[228:231], v[84:87]
	v_mfma_f32_16x16x32_bf16 v[80:83], v[156:159], v[228:231], v[80:83]
	s_setprio 0
	s_barrier
	s_add_i32 s52, 0, 0x1c000
	s_add_i32 s42, s78, s24
	v_add_u32_e32 v164, s52, v142
	v_lshl_add_u64 v[160:161], v[160:161], 0, s[56:57]
	s_mov_b32 m0, s42
	ds_read_b128 v[232:235], v164
	ds_read_b128 v[236:239], v164 offset:1024
	ds_read_b128 v[240:243], v164 offset:2048
	ds_read_b128 v[244:247], v164 offset:3072
	global_load_lds_dwordx4 v[160:161], off
	v_lshl_add_u64 v[160:161], v[162:163], 0, s[56:57]
	s_add_i32 m0, s42, 0x2000
	s_nop 0
	global_load_lds_dwordx4 v[160:161], off
	s_barrier
	s_waitcnt lgkmcnt(0)
	s_setprio 1
	s_waitcnt lgkmcnt(0)
	v_mfma_f32_16x16x32_bf16 v[110:113], v[232:235], v[174:177], v[110:113]
	v_mfma_f32_16x16x32_bf16 v[106:109], v[240:243], v[174:177], v[106:109]
	v_mfma_f32_16x16x32_bf16 v[92:95], v[232:235], v[182:185], v[92:95]
	v_mfma_f32_16x16x32_bf16 v[88:91], v[240:243], v[182:185], v[88:91]
	v_mfma_f32_16x16x32_bf16 v[76:79], v[232:235], v[190:193], v[76:79]
	v_mfma_f32_16x16x32_bf16 v[72:75], v[240:243], v[190:193], v[72:75]
	v_mfma_f32_16x16x32_bf16 v[68:71], v[232:235], v[198:201], v[68:71]
	v_mfma_f32_16x16x32_bf16 v[64:67], v[240:243], v[198:201], v[64:67]
	v_mfma_f32_16x16x32_bf16 v[110:113], v[236:239], v[178:181], v[110:113]
	v_mfma_f32_16x16x32_bf16 v[106:109], v[244:247], v[178:181], v[106:109]
	v_mfma_f32_16x16x32_bf16 v[92:95], v[236:239], v[186:189], v[92:95]
	v_mfma_f32_16x16x32_bf16 v[88:91], v[244:247], v[186:189], v[88:91]
	v_mfma_f32_16x16x32_bf16 v[76:79], v[236:239], v[194:197], v[76:79]
	v_mfma_f32_16x16x32_bf16 v[72:75], v[244:247], v[194:197], v[72:75]
	v_mfma_f32_16x16x32_bf16 v[68:71], v[236:239], v[228:231], v[68:71]
	v_mfma_f32_16x16x32_bf16 v[64:67], v[244:247], v[228:231], v[64:67]
	s_setprio 0
	s_mov_b32 m0, s60
	v_lshl_add_u64 v[160:161], v[166:167], 0, s[56:57]
	s_barrier
	ds_read_b128 v[174:177], v143 offset:49152
	ds_read_b128 v[178:181], v143 offset:50176
	ds_read_b128 v[182:185], v143 offset:51200
	ds_read_b128 v[186:189], v143 offset:52224
	ds_read_b128 v[190:193], v143 offset:53248
	ds_read_b128 v[194:197], v143 offset:54272
	ds_read_b128 v[198:201], v143 offset:55296
	ds_read_b128 v[228:231], v143 offset:56320
	global_load_lds_dwordx4 v[160:161], off
	v_lshl_add_u64 v[160:161], v[168:169], 0, s[56:57]
	s_mov_b32 m0, s61
	s_nop 0
	global_load_lds_dwordx4 v[160:161], off
	s_barrier
	s_waitcnt lgkmcnt(0)
	s_setprio 1
	s_waitcnt lgkmcnt(0)
	v_mfma_f32_16x16x32_bf16 v[60:63], v[144:147], v[174:177], v[60:63]
	v_mfma_f32_16x16x32_bf16 v[56:59], v[152:155], v[174:177], v[56:59]
	v_mfma_f32_16x16x32_bf16 v[52:55], v[144:147], v[182:185], v[52:55]
	v_mfma_f32_16x16x32_bf16 v[48:51], v[152:155], v[182:185], v[48:51]
	v_mfma_f32_16x16x32_bf16 v[36:39], v[144:147], v[190:193], v[36:39]
	v_mfma_f32_16x16x32_bf16 v[32:35], v[152:155], v[190:193], v[32:35]
	v_mfma_f32_16x16x32_bf16 v[20:23], v[144:147], v[198:201], v[20:23]
	v_mfma_f32_16x16x32_bf16 v[16:19], v[152:155], v[198:201], v[16:19]
	v_mfma_f32_16x16x32_bf16 v[60:63], v[148:151], v[178:181], v[60:63]
	v_mfma_f32_16x16x32_bf16 v[56:59], v[156:159], v[178:181], v[56:59]
	v_mfma_f32_16x16x32_bf16 v[52:55], v[148:151], v[186:189], v[52:55]
	v_mfma_f32_16x16x32_bf16 v[48:51], v[156:159], v[186:189], v[48:51]
	v_mfma_f32_16x16x32_bf16 v[36:39], v[148:151], v[194:197], v[36:39]
	v_mfma_f32_16x16x32_bf16 v[32:35], v[156:159], v[194:197], v[32:35]
	v_mfma_f32_16x16x32_bf16 v[20:23], v[148:151], v[228:231], v[20:23]
	v_mfma_f32_16x16x32_bf16 v[16:19], v[156:159], v[228:231], v[16:19]
	s_setprio 0
	s_barrier
	s_add_u32 s42, s50, 0x40080
	s_addc_u32 s43, s51, 0
	s_add_i32 s50, s52, s24
	v_lshl_add_u64 v[144:145], s[42:43], 0, v[96:97]
	s_mov_b32 m0, s50
	s_nop 0
	global_load_lds_dwordx4 v[144:145], off
	v_lshl_add_u64 v[144:145], s[42:43], 0, v[130:131]
	s_add_i32 m0, s50, 0x2000
	s_nop 0
	global_load_lds_dwordx4 v[144:145], off
	s_waitcnt vmcnt(6)
	s_barrier
	s_setprio 1
	v_mfma_f32_16x16x32_bf16 v[44:47], v[232:235], v[174:177], v[44:47]
	v_mfma_f32_16x16x32_bf16 v[40:43], v[240:243], v[174:177], v[40:43]
	v_mfma_f32_16x16x32_bf16 v[28:31], v[232:235], v[182:185], v[28:31]
	v_mfma_f32_16x16x32_bf16 v[24:27], v[240:243], v[182:185], v[24:27]
	v_mfma_f32_16x16x32_bf16 v[12:15], v[232:235], v[190:193], v[12:15]
	v_mfma_f32_16x16x32_bf16 v[8:11], v[240:243], v[190:193], v[8:11]
	v_mfma_f32_16x16x32_bf16 v[4:7], v[232:235], v[198:201], v[4:7]
	v_mfma_f32_16x16x32_bf16 v[0:3], v[240:243], v[198:201], v[0:3]
	v_mfma_f32_16x16x32_bf16 v[44:47], v[236:239], v[178:181], v[44:47]
	v_mfma_f32_16x16x32_bf16 v[40:43], v[244:247], v[178:181], v[40:43]
	v_mfma_f32_16x16x32_bf16 v[28:31], v[236:239], v[186:189], v[28:31]
	v_mfma_f32_16x16x32_bf16 v[24:27], v[244:247], v[186:189], v[24:27]
	v_mfma_f32_16x16x32_bf16 v[12:15], v[236:239], v[194:197], v[12:15]
	v_mfma_f32_16x16x32_bf16 v[8:11], v[244:247], v[194:197], v[8:11]
	v_mfma_f32_16x16x32_bf16 v[4:7], v[236:239], v[228:231], v[4:7]
	v_mfma_f32_16x16x32_bf16 v[0:3], v[244:247], v[228:231], v[0:3]
	s_setprio 0
	s_add_i32 s77, s77, 2
	s_add_u32 s48, s48, 0x100
	s_addc_u32 s49, s49, 0
	s_add_u32 s75, s75, 0x100
	s_addc_u32 s76, s76, 0
	s_cmp_gt_u32 s77, 13
	s_barrier

.LBB0_441:
	s_ashr_i32 s31, s30, 31
	v_mov_b64_e32 v[0:1], 0x3c0
	s_lshl_b64 s[42:43], s[30:31], 19
	v_cmp_lt_i64_e32 vcc, s[44:45], v[0:1]
	s_add_u32 s44, s22, s42
	s_addc_u32 s45, s23, s43
	s_and_b64 s[42:43], vcc, exec
	s_cselect_b32 s31, s45, s49
	s_cselect_b32 s73, s44, s48
	s_ashr_i32 s1, s0, 31
	s_lshl_b64 s[42:43], s[0:1], 19
	v_readlane_b32 s1, v252, 27
	s_add_u32 s46, s1, s42
	v_readlane_b32 s1, v252, 28
	s_addc_u32 s47, s1, s43
	s_and_b64 s[42:43], vcc, exec
	s_cselect_b32 s1, s47, s51
	s_cselect_b32 s74, s46, s50
	s_add_u32 s48, s48, 0x40080
	s_addc_u32 s49, s49, 0
	s_add_u32 s75, s50, 0x100
	s_addc_u32 s76, s51, 0
	s_mov_b32 s77, -2
	s_add_u32 s42, s48, 0xfffc0080
	s_addc_u32 s43, s49, -1
	s_add_i32 s78, 0, 0x10000
	v_add_u32_e32 v156, s78, v142
	ds_read_b128 v[144:147], v156
	ds_read_b128 v[148:151], v156 offset:1024
	ds_read_b128 v[152:155], v156 offset:2048
	ds_read_b128 v[156:159], v156 offset:3072
	s_cmp_eq_u32 s77, 12
	s_cselect_b32 s53, s31, s43
	s_cselect_b32 s52, s73, s42
	s_cselect_b32 s51, s1, s76
	s_cselect_b32 s50, s74, s75
	v_lshl_add_u64 v[160:161], s[48:49], 0, v[136:137]
	s_add_i32 m0, s36, 0xc000
	ds_read_b128 v[174:177], v143
	ds_read_b128 v[178:181], v143 offset:1024
	ds_read_b128 v[182:185], v143 offset:2048
	ds_read_b128 v[186:189], v143 offset:3072
	ds_read_b128 v[190:193], v143 offset:4096
	ds_read_b128 v[194:197], v143 offset:5120
	ds_read_b128 v[198:201], v143 offset:6144
	ds_read_b128 v[228:231], v143 offset:7168
	global_load_lds_dwordx4 v[160:161], off
	v_lshl_add_u64 v[160:161], s[48:49], 0, v[138:139]
	s_add_i32 m0, s36, 0xe000
	s_nop 0
	global_load_lds_dwordx4 v[160:161], off
	s_waitcnt lgkmcnt(8)
	s_barrier
	s_waitcnt lgkmcnt(0)
	s_setprio 1
	s_waitcnt lgkmcnt(0)
	v_mfma_f32_16x16x32_bf16 v[126:129], v[144:147], v[174:177], 0
	v_mfma_f32_16x16x32_bf16 v[122:125], v[152:155], v[174:177], 0
	v_mfma_f32_16x16x32_bf16 v[118:121], v[144:147], v[182:185], 0
	v_mfma_f32_16x16x32_bf16 v[114:117], v[152:155], v[182:185], 0
	v_mfma_f32_16x16x32_bf16 v[102:105], v[144:147], v[190:193], 0
	v_mfma_f32_16x16x32_bf16 v[98:101], v[152:155], v[190:193], 0
	v_mfma_f32_16x16x32_bf16 v[84:87], v[144:147], v[198:201], 0
	v_mfma_f32_16x16x32_bf16 v[80:83], v[152:155], v[198:201], 0
	v_mfma_f32_16x16x32_bf16 v[126:129], v[148:151], v[178:181], v[126:129]
	v_mfma_f32_16x16x32_bf16 v[122:125], v[156:159], v[178:181], v[122:125]
	v_mfma_f32_16x16x32_bf16 v[118:121], v[148:151], v[186:189], v[118:121]
	v_mfma_f32_16x16x32_bf16 v[114:117], v[156:159], v[186:189], v[114:117]
	v_mfma_f32_16x16x32_bf16 v[102:105], v[148:151], v[194:197], v[102:105]
	v_mfma_f32_16x16x32_bf16 v[98:101], v[156:159], v[194:197], v[98:101]
	v_mfma_f32_16x16x32_bf16 v[84:87], v[148:151], v[228:231], v[84:87]
	v_mfma_f32_16x16x32_bf16 v[80:83], v[156:159], v[228:231], v[80:83]
	s_setprio 0
	s_barrier
	s_add_i32 s79, 0, 0x14000
	v_add_u32_e32 v160, s79, v142
	s_add_i32 s42, s78, s24
	ds_read_b128 v[232:235], v160
	ds_read_b128 v[236:239], v160 offset:1024
	ds_read_b128 v[240:243], v160 offset:2048
	ds_read_b128 v[244:247], v160 offset:3072
	v_lshl_add_u64 v[160:161], s[50:51], 0, v[96:97]
	s_mov_b32 m0, s42
	v_lshl_add_u64 v[162:163], s[50:51], 0, v[130:131]
	global_load_lds_dwordx4 v[160:161], off
	s_add_i32 m0, s42, 0x2000
	s_nop 0
	global_load_lds_dwordx4 v[162:163], off
	s_barrier
	s_waitcnt lgkmcnt(0)
	s_setprio 1
	s_waitcnt lgkmcnt(0)
	v_mfma_f32_16x16x32_bf16 v[110:113], v[232:235], v[174:177], 0
	v_mfma_f32_16x16x32_bf16 v[106:109], v[240:243], v[174:177], 0
	v_mfma_f32_16x16x32_bf16 v[92:95], v[232:235], v[182:185], 0
	v_mfma_f32_16x16x32_bf16 v[88:91], v[240:243], v[182:185], 0
	v_mfma_f32_16x16x32_bf16 v[76:79], v[232:235], v[190:193], 0
	v_mfma_f32_16x16x32_bf16 v[72:75], v[240:243], v[190:193], 0
	v_mfma_f32_16x16x32_bf16 v[68:71], v[232:235], v[198:201], 0
	v_mfma_f32_16x16x32_bf16 v[64:67], v[240:243], v[198:201], 0
	v_mfma_f32_16x16x32_bf16 v[110:113], v[236:239], v[178:181], v[110:113]
	v_mfma_f32_16x16x32_bf16 v[106:109], v[244:247], v[178:181], v[106:109]
	v_mfma_f32_16x16x32_bf16 v[92:95], v[236:239], v[186:189], v[92:95]
	v_mfma_f32_16x16x32_bf16 v[88:91], v[244:247], v[186:189], v[88:91]
	v_mfma_f32_16x16x32_bf16 v[76:79], v[236:239], v[194:197], v[76:79]
	v_mfma_f32_16x16x32_bf16 v[72:75], v[244:247], v[194:197], v[72:75]
	v_mfma_f32_16x16x32_bf16 v[68:71], v[236:239], v[228:231], v[68:71]
	v_mfma_f32_16x16x32_bf16 v[64:67], v[244:247], v[228:231], v[64:67]
	s_setprio 0
	s_mov_b32 m0, s36
	v_lshl_add_u64 v[166:167], s[52:53], 0, v[134:135]
	s_barrier
	ds_read_b128 v[174:177], v143 offset:16384
	ds_read_b128 v[178:181], v143 offset:17408
	ds_read_b128 v[182:185], v143 offset:18432
	ds_read_b128 v[186:189], v143 offset:19456
	ds_read_b128 v[190:193], v143 offset:20480
	ds_read_b128 v[194:197], v143 offset:21504
	ds_read_b128 v[198:201], v143 offset:22528
	ds_read_b128 v[228:231], v143 offset:23552
	global_load_lds_dwordx4 v[166:167], off
	v_lshl_add_u64 v[168:169], s[52:53], 0, v[132:133]
	s_mov_b32 m0, s37
	s_nop 0
	global_load_lds_dwordx4 v[168:169], off
	s_barrier
	s_waitcnt lgkmcnt(0)
	s_setprio 1
	s_waitcnt lgkmcnt(0)
	v_mfma_f32_16x16x32_bf16 v[60:63], v[144:147], v[174:177], 0
	v_mfma_f32_16x16x32_bf16 v[56:59], v[152:155], v[174:177], 0
	v_mfma_f32_16x16x32_bf16 v[52:55], v[144:147], v[182:185], 0
	v_mfma_f32_16x16x32_bf16 v[48:51], v[152:155], v[182:185], 0
	v_mfma_f32_16x16x32_bf16 v[36:39], v[144:147], v[190:193], 0
	v_mfma_f32_16x16x32_bf16 v[32:35], v[152:155], v[190:193], 0
	v_mfma_f32_16x16x32_bf16 v[20:23], v[144:147], v[198:201], 0
	v_mfma_f32_16x16x32_bf16 v[16:19], v[152:155], v[198:201], 0
	v_mfma_f32_16x16x32_bf16 v[60:63], v[148:151], v[178:181], v[60:63]
	v_mfma_f32_16x16x32_bf16 v[56:59], v[156:159], v[178:181], v[56:59]
	v_mfma_f32_16x16x32_bf16 v[52:55], v[148:151], v[186:189], v[52:55]
	v_mfma_f32_16x16x32_bf16 v[48:51], v[156:159], v[186:189], v[48:51]
	v_mfma_f32_16x16x32_bf16 v[36:39], v[148:151], v[194:197], v[36:39]
	v_mfma_f32_16x16x32_bf16 v[32:35], v[156:159], v[194:197], v[32:35]
	v_mfma_f32_16x16x32_bf16 v[20:23], v[148:151], v[228:231], v[20:23]
	v_mfma_f32_16x16x32_bf16 v[16:19], v[156:159], v[228:231], v[16:19]
	s_setprio 0
	s_barrier
	s_add_u32 s42, s50, 0x40000
	s_addc_u32 s43, s51, 0
	s_add_i32 s78, s79, s24
	v_lshl_add_u64 v[144:145], s[42:43], 0, v[96:97]
	s_mov_b32 m0, s78
	s_nop 0
	global_load_lds_dwordx4 v[144:145], off
	v_lshl_add_u64 v[144:145], s[42:43], 0, v[130:131]
	s_add_i32 m0, s78, 0x2000
	s_nop 0
	global_load_lds_dwordx4 v[144:145], off
	s_waitcnt vmcnt(6)
	s_barrier
	s_setprio 1
	v_mfma_f32_16x16x32_bf16 v[44:47], v[232:235], v[174:177], 0
	v_mfma_f32_16x16x32_bf16 v[40:43], v[240:243], v[174:177], 0
	v_mfma_f32_16x16x32_bf16 v[28:31], v[232:235], v[182:185], 0
	v_mfma_f32_16x16x32_bf16 v[24:27], v[240:243], v[182:185], 0
	v_mfma_f32_16x16x32_bf16 v[12:15], v[232:235], v[190:193], 0
	v_mfma_f32_16x16x32_bf16 v[8:11], v[240:243], v[190:193], 0
	v_mfma_f32_16x16x32_bf16 v[4:7], v[232:235], v[198:201], 0
	v_mfma_f32_16x16x32_bf16 v[0:3], v[240:243], v[198:201], 0
	v_mfma_f32_16x16x32_bf16 v[44:47], v[236:239], v[178:181], v[44:47]
	v_mfma_f32_16x16x32_bf16 v[40:43], v[244:247], v[178:181], v[40:43]
	v_mfma_f32_16x16x32_bf16 v[28:31], v[236:239], v[186:189], v[28:31]
	v_mfma_f32_16x16x32_bf16 v[24:27], v[244:247], v[186:189], v[24:27]
	v_mfma_f32_16x16x32_bf16 v[12:15], v[236:239], v[194:197], v[12:15]
	v_mfma_f32_16x16x32_bf16 v[8:11], v[244:247], v[194:197], v[8:11]
	v_mfma_f32_16x16x32_bf16 v[4:7], v[236:239], v[228:231], v[4:7]
	v_mfma_f32_16x16x32_bf16 v[0:3], v[244:247], v[228:231], v[0:3]
	s_setprio 0
	s_add_i32 s78, 0, 0x18000
	v_add_u32_e32 v156, s78, v142
	s_barrier
	ds_read_b128 v[144:147], v156
	ds_read_b128 v[148:151], v156 offset:1024
	ds_read_b128 v[152:155], v156 offset:2048
	ds_read_b128 v[156:159], v156 offset:3072
	s_add_u32 s42, s52, 0x40000
	s_addc_u32 s43, s53, 0
	s_mov_b32 m0, s58
	v_lshl_add_u64 v[202:203], s[42:43], 0, v[134:135]
	ds_read_b128 v[174:177], v143 offset:32768
	ds_read_b128 v[178:181], v143 offset:33792
	ds_read_b128 v[182:185], v143 offset:34816
	ds_read_b128 v[186:189], v143 offset:35840
	ds_read_b128 v[190:193], v143 offset:36864
	ds_read_b128 v[194:197], v143 offset:37888
	ds_read_b128 v[198:201], v143 offset:38912
	ds_read_b128 v[228:231], v143 offset:39936
	global_load_lds_dwordx4 v[202:203], off
	v_lshl_add_u64 v[202:203], s[42:43], 0, v[132:133]
	s_mov_b32 m0, s59
	s_nop 0
	global_load_lds_dwordx4 v[202:203], off
	s_waitcnt lgkmcnt(8)
	s_barrier
	s_waitcnt lgkmcnt(0)
	s_setprio 1
	s_waitcnt lgkmcnt(0)
	v_mfma_f32_16x16x32_bf16 v[126:129], v[144:147], v[174:177], v[126:129]
	v_mfma_f32_16x16x32_bf16 v[122:125], v[152:155], v[174:177], v[122:125]
	v_mfma_f32_16x16x32_bf16 v[118:121], v[144:147], v[182:185], v[118:121]
	v_mfma_f32_16x16x32_bf16 v[114:117], v[152:155], v[182:185], v[114:117]
	v_mfma_f32_16x16x32_bf16 v[102:105], v[144:147], v[190:193], v[102:105]
	v_mfma_f32_16x16x32_bf16 v[98:101], v[152:155], v[190:193], v[98:101]
	v_mfma_f32_16x16x32_bf16 v[84:87], v[144:147], v[198:201], v[84:87]
	v_mfma_f32_16x16x32_bf16 v[80:83], v[152:155], v[198:201], v[80:83]
	v_mfma_f32_16x16x32_bf16 v[126:129], v[148:151], v[178:181], v[126:129]
	v_mfma_f32_16x16x32_bf16 v[122:125], v[156:159], v[178:181], v[122:125]
	v_mfma_f32_16x16x32_bf16 v[118:121], v[148:151], v[186:189], v[118:121]
	v_mfma_f32_16x16x32_bf16 v[114:117], v[156:159], v[186:189], v[114:117]
	v_mfma_f32_16x16x32_bf16 v[102:105], v[148:151], v[194:197], v[102:105]
	v_mfma_f32_16x16x32_bf16 v[98:101], v[156:159], v[194:197], v[98:101]
	v_mfma_f32_16x16x32_bf16 v[84:87], v[148:151], v[228:231], v[84:87]
	v_mfma_f32_16x16x32_bf16 v[80:83], v[156:159], v[228:231], v[80:83]
	s_setprio 0
	s_barrier
	s_add_i32 s52, 0, 0x1c000
	s_add_i32 s42, s78, s24
	v_add_u32_e32 v164, s52, v142
	v_lshl_add_u64 v[160:161], v[160:161], 0, s[56:57]
	s_mov_b32 m0, s42
	ds_read_b128 v[232:235], v164
	ds_read_b128 v[236:239], v164 offset:1024
	ds_read_b128 v[240:243], v164 offset:2048
	ds_read_b128 v[244:247], v164 offset:3072
	global_load_lds_dwordx4 v[160:161], off
	v_lshl_add_u64 v[160:161], v[162:163], 0, s[56:57]
	s_add_i32 m0, s42, 0x2000
	s_nop 0
	global_load_lds_dwordx4 v[160:161], off
	s_barrier
	s_waitcnt lgkmcnt(0)
	s_setprio 1
	s_waitcnt lgkmcnt(0)
	v_mfma_f32_16x16x32_bf16 v[110:113], v[232:235], v[174:177], v[110:113]
	v_mfma_f32_16x16x32_bf16 v[106:109], v[240:243], v[174:177], v[106:109]
	v_mfma_f32_16x16x32_bf16 v[92:95], v[232:235], v[182:185], v[92:95]
	v_mfma_f32_16x16x32_bf16 v[88:91], v[240:243], v[182:185], v[88:91]
	v_mfma_f32_16x16x32_bf16 v[76:79], v[232:235], v[190:193], v[76:79]
	v_mfma_f32_16x16x32_bf16 v[72:75], v[240:243], v[190:193], v[72:75]
	v_mfma_f32_16x16x32_bf16 v[68:71], v[232:235], v[198:201], v[68:71]
	v_mfma_f32_16x16x32_bf16 v[64:67], v[240:243], v[198:201], v[64:67]
	v_mfma_f32_16x16x32_bf16 v[110:113], v[236:239], v[178:181], v[110:113]
	v_mfma_f32_16x16x32_bf16 v[106:109], v[244:247], v[178:181], v[106:109]
	v_mfma_f32_16x16x32_bf16 v[92:95], v[236:239], v[186:189], v[92:95]
	v_mfma_f32_16x16x32_bf16 v[88:91], v[244:247], v[186:189], v[88:91]
	v_mfma_f32_16x16x32_bf16 v[76:79], v[236:239], v[194:197], v[76:79]
	v_mfma_f32_16x16x32_bf16 v[72:75], v[244:247], v[194:197], v[72:75]
	v_mfma_f32_16x16x32_bf16 v[68:71], v[236:239], v[228:231], v[68:71]
	v_mfma_f32_16x16x32_bf16 v[64:67], v[244:247], v[228:231], v[64:67]
	s_setprio 0
	s_mov_b32 m0, s60
	v_lshl_add_u64 v[160:161], v[166:167], 0, s[56:57]
	s_barrier
	ds_read_b128 v[174:177], v143 offset:49152
	ds_read_b128 v[178:181], v143 offset:50176
	ds_read_b128 v[182:185], v143 offset:51200
	ds_read_b128 v[186:189], v143 offset:52224
	ds_read_b128 v[190:193], v143 offset:53248
	ds_read_b128 v[194:197], v143 offset:54272
	ds_read_b128 v[198:201], v143 offset:55296
	ds_read_b128 v[228:231], v143 offset:56320
	global_load_lds_dwordx4 v[160:161], off
	v_lshl_add_u64 v[160:161], v[168:169], 0, s[56:57]
	s_mov_b32 m0, s61
	s_nop 0
	global_load_lds_dwordx4 v[160:161], off
	s_barrier
	s_waitcnt lgkmcnt(0)
	s_setprio 1
	s_waitcnt lgkmcnt(0)
	v_mfma_f32_16x16x32_bf16 v[60:63], v[144:147], v[174:177], v[60:63]
	v_mfma_f32_16x16x32_bf16 v[56:59], v[152:155], v[174:177], v[56:59]
	v_mfma_f32_16x16x32_bf16 v[52:55], v[144:147], v[182:185], v[52:55]
	v_mfma_f32_16x16x32_bf16 v[48:51], v[152:155], v[182:185], v[48:51]
	v_mfma_f32_16x16x32_bf16 v[36:39], v[144:147], v[190:193], v[36:39]
	v_mfma_f32_16x16x32_bf16 v[32:35], v[152:155], v[190:193], v[32:35]
	v_mfma_f32_16x16x32_bf16 v[20:23], v[144:147], v[198:201], v[20:23]
	v_mfma_f32_16x16x32_bf16 v[16:19], v[152:155], v[198:201], v[16:19]
	v_mfma_f32_16x16x32_bf16 v[60:63], v[148:151], v[178:181], v[60:63]
	v_mfma_f32_16x16x32_bf16 v[56:59], v[156:159], v[178:181], v[56:59]
	v_mfma_f32_16x16x32_bf16 v[52:55], v[148:151], v[186:189], v[52:55]
	v_mfma_f32_16x16x32_bf16 v[48:51], v[156:159], v[186:189], v[48:51]
	v_mfma_f32_16x16x32_bf16 v[36:39], v[148:151], v[194:197], v[36:39]
	v_mfma_f32_16x16x32_bf16 v[32:35], v[156:159], v[194:197], v[32:35]
	v_mfma_f32_16x16x32_bf16 v[20:23], v[148:151], v[228:231], v[20:23]
	v_mfma_f32_16x16x32_bf16 v[16:19], v[156:159], v[228:231], v[16:19]
	s_setprio 0
	s_barrier
	s_add_u32 s42, s50, 0x40080
	s_addc_u32 s43, s51, 0
	s_add_i32 s50, s52, s24
	v_lshl_add_u64 v[144:145], s[42:43], 0, v[96:97]
	s_mov_b32 m0, s50
	s_nop 0
	global_load_lds_dwordx4 v[144:145], off
	v_lshl_add_u64 v[144:145], s[42:43], 0, v[130:131]
	s_add_i32 m0, s50, 0x2000
	s_nop 0
	global_load_lds_dwordx4 v[144:145], off
	s_waitcnt vmcnt(6)
	s_barrier
	s_setprio 1
	v_mfma_f32_16x16x32_bf16 v[44:47], v[232:235], v[174:177], v[44:47]
	v_mfma_f32_16x16x32_bf16 v[40:43], v[240:243], v[174:177], v[40:43]
	v_mfma_f32_16x16x32_bf16 v[28:31], v[232:235], v[182:185], v[28:31]
	v_mfma_f32_16x16x32_bf16 v[24:27], v[240:243], v[182:185], v[24:27]
	v_mfma_f32_16x16x32_bf16 v[12:15], v[232:235], v[190:193], v[12:15]
	v_mfma_f32_16x16x32_bf16 v[8:11], v[240:243], v[190:193], v[8:11]
	v_mfma_f32_16x16x32_bf16 v[4:7], v[232:235], v[198:201], v[4:7]
	v_mfma_f32_16x16x32_bf16 v[0:3], v[240:243], v[198:201], v[0:3]
	v_mfma_f32_16x16x32_bf16 v[44:47], v[236:239], v[178:181], v[44:47]
	v_mfma_f32_16x16x32_bf16 v[40:43], v[244:247], v[178:181], v[40:43]
	v_mfma_f32_16x16x32_bf16 v[28:31], v[236:239], v[186:189], v[28:31]
	v_mfma_f32_16x16x32_bf16 v[24:27], v[244:247], v[186:189], v[24:27]
	v_mfma_f32_16x16x32_bf16 v[12:15], v[236:239], v[194:197], v[12:15]
	v_mfma_f32_16x16x32_bf16 v[8:11], v[244:247], v[194:197], v[8:11]
	v_mfma_f32_16x16x32_bf16 v[4:7], v[236:239], v[228:231], v[4:7]
	v_mfma_f32_16x16x32_bf16 v[0:3], v[244:247], v[228:231], v[0:3]
	s_setprio 0
	s_add_i32 s77, s77, 2
	s_add_u32 s48, s48, 0x100
	s_addc_u32 s49, s49, 0
	s_add_u32 s75, s75, 0x100
	s_addc_u32 s76, s76, 0
	s_cmp_gt_u32 s77, 13
	s_barrier

.LBB0_481:
	s_add_u32 s50, s46, 0x100
	s_addc_u32 s51, s47, 0
	s_mov_b32 s52, -2
	s_add_u32 s0, s30, 0x100
	s_addc_u32 s1, s31, 0
	s_add_i32 s42, 0, 0x10000
	v_add_u32_e32 v96, s42, v229
	ds_read_b128 v[98:101], v96
	ds_read_b128 v[102:105], v96 offset:1024
	ds_read_b128 v[106:109], v96 offset:2048
	ds_read_b128 v[110:113], v96 offset:3072
	s_cmp_eq_u32 s52, 40
	s_cselect_b32 s47, s71, s1
	s_cselect_b32 s46, s70, s0
	s_cselect_b32 s45, s97, s51
	s_cselect_b32 s44, s96, s50
	v_lshl_add_u64 v[138:139], s[30:31], 0, v[146:147]
	s_add_i32 m0, s72, 0xc000
	ds_read_b128 v[114:117], v230
	ds_read_b128 v[118:121], v230 offset:1024
	ds_read_b128 v[122:125], v230 offset:2048
	ds_read_b128 v[126:129], v230 offset:3072
	ds_read_b128 v[130:133], v230 offset:4096
	ds_read_b128 v[134:137], v230 offset:5120
	global_load_lds_dwordx4 v[138:139], off
	v_lshl_add_u64 v[138:139], s[30:31], 0, v[148:149]
	s_add_i32 m0, s72, 0xe000
	s_nop 0
	global_load_lds_dwordx4 v[138:139], off
	s_waitcnt lgkmcnt(6)
	s_barrier
	s_waitcnt lgkmcnt(0)
	s_setprio 1
	s_waitcnt lgkmcnt(0)
	v_mfma_f32_16x16x32_bf16 v[92:95], v[98:101], v[114:117], 0
	v_mfma_f32_16x16x32_bf16 v[80:83], v[106:109], v[114:117], 0
	v_mfma_f32_16x16x32_bf16 v[88:91], v[98:101], v[122:125], 0
	v_mfma_f32_16x16x32_bf16 v[68:71], v[106:109], v[122:125], 0
	v_mfma_f32_16x16x32_bf16 v[84:87], v[98:101], v[130:133], 0
	v_mfma_f32_16x16x32_bf16 v[60:63], v[106:109], v[130:133], 0
	v_mfma_f32_16x16x32_bf16 v[92:95], v[102:105], v[118:121], v[92:95]
	v_mfma_f32_16x16x32_bf16 v[80:83], v[110:113], v[118:121], v[80:83]
	v_mfma_f32_16x16x32_bf16 v[88:91], v[102:105], v[126:129], v[88:91]
	v_mfma_f32_16x16x32_bf16 v[68:71], v[110:113], v[126:129], v[68:71]
	v_mfma_f32_16x16x32_bf16 v[84:87], v[102:105], v[134:137], v[84:87]
	v_mfma_f32_16x16x32_bf16 v[60:63], v[110:113], v[134:137], v[60:63]
	s_setprio 0
	s_barrier
	s_add_i32 s43, 0, 0x14000
	s_add_i32 s30, s42, s37
	v_add_u32_e32 v96, s43, v229
	v_lshl_add_u64 v[162:163], s[44:45], 0, v[144:145]
	s_mov_b32 m0, s30
	ds_read_b128 v[138:141], v96
	ds_read_b128 v[150:153], v96 offset:1024
	ds_read_b128 v[154:157], v96 offset:2048
	ds_read_b128 v[158:161], v96 offset:3072
	global_load_lds_dwordx4 v[162:163], off
	v_lshl_add_u64 v[166:167], s[44:45], 0, v[142:143]
	s_add_i32 m0, s30, 0x2000
	s_nop 0
	global_load_lds_dwordx4 v[166:167], off
	s_barrier
	s_waitcnt lgkmcnt(0)
	s_setprio 1
	s_waitcnt lgkmcnt(0)
	v_mfma_f32_16x16x32_bf16 v[48:51], v[138:141], v[114:117], 0
	v_mfma_f32_16x16x32_bf16 v[28:31], v[154:157], v[114:117], 0
	v_mfma_f32_16x16x32_bf16 v[40:43], v[138:141], v[122:125], 0
	v_mfma_f32_16x16x32_bf16 v[20:23], v[154:157], v[122:125], 0
	v_mfma_f32_16x16x32_bf16 v[36:39], v[138:141], v[130:133], 0
	v_mfma_f32_16x16x32_bf16 v[12:15], v[154:157], v[130:133], 0
	v_mfma_f32_16x16x32_bf16 v[48:51], v[150:153], v[118:121], v[48:51]
	v_mfma_f32_16x16x32_bf16 v[28:31], v[158:161], v[118:121], v[28:31]
	v_mfma_f32_16x16x32_bf16 v[40:43], v[150:153], v[126:129], v[40:43]
	v_mfma_f32_16x16x32_bf16 v[20:23], v[158:161], v[126:129], v[20:23]
	v_mfma_f32_16x16x32_bf16 v[36:39], v[150:153], v[134:137], v[36:39]
	v_mfma_f32_16x16x32_bf16 v[12:15], v[158:161], v[134:137], v[12:15]
	s_setprio 0
	s_mov_b32 m0, s72
	v_lshl_add_u64 v[168:169], s[46:47], 0, v[144:145]
	s_barrier
	ds_read_b128 v[114:117], v230 offset:16384
	ds_read_b128 v[118:121], v230 offset:17408
	ds_read_b128 v[122:125], v230 offset:18432
	ds_read_b128 v[126:129], v230 offset:19456
	ds_read_b128 v[130:133], v230 offset:20480
	ds_read_b128 v[134:137], v230 offset:21504
	global_load_lds_dwordx4 v[168:169], off
	v_lshl_add_u64 v[174:175], s[46:47], 0, v[142:143]
	s_mov_b32 m0, s73
	s_nop 0
	global_load_lds_dwordx4 v[174:175], off
	s_barrier
	s_waitcnt lgkmcnt(0)
	s_setprio 1
	s_waitcnt lgkmcnt(0)
	v_mfma_f32_16x16x32_bf16 v[76:79], v[98:101], v[114:117], 0
	v_mfma_f32_16x16x32_bf16 v[56:59], v[106:109], v[114:117], 0
	v_mfma_f32_16x16x32_bf16 v[72:75], v[98:101], v[122:125], 0
	v_mfma_f32_16x16x32_bf16 v[52:55], v[106:109], v[122:125], 0
	v_mfma_f32_16x16x32_bf16 v[64:67], v[98:101], v[130:133], 0
	v_mfma_f32_16x16x32_bf16 v[44:47], v[106:109], v[130:133], 0
	v_mfma_f32_16x16x32_bf16 v[76:79], v[102:105], v[118:121], v[76:79]
	v_mfma_f32_16x16x32_bf16 v[56:59], v[110:113], v[118:121], v[56:59]
	v_mfma_f32_16x16x32_bf16 v[72:75], v[102:105], v[126:129], v[72:75]
	v_mfma_f32_16x16x32_bf16 v[52:55], v[110:113], v[126:129], v[52:55]
	v_mfma_f32_16x16x32_bf16 v[64:67], v[102:105], v[134:137], v[64:67]
	v_mfma_f32_16x16x32_bf16 v[44:47], v[110:113], v[134:137], v[44:47]
	s_setprio 0
	s_barrier
	s_add_u32 s30, s44, 0xb0000
	s_addc_u32 s31, s45, 0
	s_add_i32 s42, s43, s37
	v_lshl_add_u64 v[98:99], s[30:31], 0, v[144:145]
	s_mov_b32 m0, s42
	s_nop 0
	global_load_lds_dwordx4 v[98:99], off
	v_lshl_add_u64 v[98:99], s[30:31], 0, v[142:143]
	s_add_i32 m0, s42, 0x2000
	s_nop 0
	global_load_lds_dwordx4 v[98:99], off
	s_waitcnt vmcnt(6)
	s_barrier
	s_setprio 1
	v_mfma_f32_16x16x32_bf16 v[32:35], v[138:141], v[114:117], 0
	v_mfma_f32_16x16x32_bf16 v[8:11], v[154:157], v[114:117], 0
	v_mfma_f32_16x16x32_bf16 v[24:27], v[138:141], v[122:125], 0
	v_mfma_f32_16x16x32_bf16 v[4:7], v[154:157], v[122:125], 0
	v_mfma_f32_16x16x32_bf16 v[16:19], v[138:141], v[130:133], 0
	v_mfma_f32_16x16x32_bf16 v[0:3], v[154:157], v[130:133], 0
	v_mfma_f32_16x16x32_bf16 v[32:35], v[150:153], v[118:121], v[32:35]
	v_mfma_f32_16x16x32_bf16 v[8:11], v[158:161], v[118:121], v[8:11]
	v_mfma_f32_16x16x32_bf16 v[24:27], v[150:153], v[126:129], v[24:27]
	v_mfma_f32_16x16x32_bf16 v[4:7], v[158:161], v[126:129], v[4:7]
	v_mfma_f32_16x16x32_bf16 v[16:19], v[150:153], v[134:137], v[16:19]
	v_mfma_f32_16x16x32_bf16 v[0:3], v[158:161], v[134:137], v[0:3]
	s_setprio 0
	s_add_i32 s42, 0, 0x18000
	v_add_u32_e32 v96, s42, v229
	s_barrier
	ds_read_b128 v[98:101], v96
	ds_read_b128 v[102:105], v96 offset:1024
	ds_read_b128 v[106:109], v96 offset:2048
	ds_read_b128 v[110:113], v96 offset:3072
	s_add_u32 s30, s46, 0x84000
	s_addc_u32 s31, s47, 0
	s_mov_b32 m0, s74
	v_lshl_add_u64 v[138:139], s[30:31], 0, v[144:145]
	ds_read_b128 v[114:117], v230 offset:32768
	ds_read_b128 v[118:121], v230 offset:33792
	ds_read_b128 v[122:125], v230 offset:34816
	ds_read_b128 v[126:129], v230 offset:35840
	ds_read_b128 v[130:133], v230 offset:36864
	ds_read_b128 v[134:137], v230 offset:37888
	global_load_lds_dwordx4 v[138:139], off
	v_lshl_add_u64 v[138:139], s[30:31], 0, v[142:143]
	s_mov_b32 m0, s75
	s_nop 0
	global_load_lds_dwordx4 v[138:139], off
	s_waitcnt lgkmcnt(6)
	s_barrier
	s_waitcnt lgkmcnt(0)
	s_setprio 1
	s_waitcnt lgkmcnt(0)
	v_mfma_f32_16x16x32_bf16 v[92:95], v[98:101], v[114:117], v[92:95]
	v_mfma_f32_16x16x32_bf16 v[80:83], v[106:109], v[114:117], v[80:83]
	v_mfma_f32_16x16x32_bf16 v[88:91], v[98:101], v[122:125], v[88:91]
	v_mfma_f32_16x16x32_bf16 v[68:71], v[106:109], v[122:125], v[68:71]
	v_mfma_f32_16x16x32_bf16 v[84:87], v[98:101], v[130:133], v[84:87]
	v_mfma_f32_16x16x32_bf16 v[60:63], v[106:109], v[130:133], v[60:63]
	v_mfma_f32_16x16x32_bf16 v[92:95], v[102:105], v[118:121], v[92:95]
	v_mfma_f32_16x16x32_bf16 v[80:83], v[110:113], v[118:121], v[80:83]
	v_mfma_f32_16x16x32_bf16 v[88:91], v[102:105], v[126:129], v[88:91]
	v_mfma_f32_16x16x32_bf16 v[68:71], v[110:113], v[126:129], v[68:71]
	v_mfma_f32_16x16x32_bf16 v[84:87], v[102:105], v[134:137], v[84:87]
	v_mfma_f32_16x16x32_bf16 v[60:63], v[110:113], v[134:137], v[60:63]
	s_setprio 0
	s_barrier
	s_add_i32 s43, 0, 0x1c000
	s_add_i32 s30, s42, s37
	v_add_u32_e32 v96, s43, v229
	v_lshl_add_u64 v[162:163], v[162:163], 0, s[56:57]
	s_mov_b32 m0, s30
	ds_read_b128 v[138:141], v96
	ds_read_b128 v[150:153], v96 offset:1024
	ds_read_b128 v[154:157], v96 offset:2048
	ds_read_b128 v[158:161], v96 offset:3072
	global_load_lds_dwordx4 v[162:163], off
	v_lshl_add_u64 v[162:163], v[166:167], 0, s[56:57]
	s_add_i32 m0, s30, 0x2000
	s_nop 0
	global_load_lds_dwordx4 v[162:163], off
	s_barrier
	s_waitcnt lgkmcnt(0)
	s_setprio 1
	s_waitcnt lgkmcnt(0)
	v_mfma_f32_16x16x32_bf16 v[48:51], v[138:141], v[114:117], v[48:51]
	v_mfma_f32_16x16x32_bf16 v[28:31], v[154:157], v[114:117], v[28:31]
	v_mfma_f32_16x16x32_bf16 v[40:43], v[138:141], v[122:125], v[40:43]
	v_mfma_f32_16x16x32_bf16 v[20:23], v[154:157], v[122:125], v[20:23]
	v_mfma_f32_16x16x32_bf16 v[36:39], v[138:141], v[130:133], v[36:39]
	v_mfma_f32_16x16x32_bf16 v[12:15], v[154:157], v[130:133], v[12:15]
	v_mfma_f32_16x16x32_bf16 v[48:51], v[150:153], v[118:121], v[48:51]
	v_mfma_f32_16x16x32_bf16 v[28:31], v[158:161], v[118:121], v[28:31]
	v_mfma_f32_16x16x32_bf16 v[40:43], v[150:153], v[126:129], v[40:43]
	v_mfma_f32_16x16x32_bf16 v[20:23], v[158:161], v[126:129], v[20:23]
	v_mfma_f32_16x16x32_bf16 v[36:39], v[150:153], v[134:137], v[36:39]
	v_mfma_f32_16x16x32_bf16 v[12:15], v[158:161], v[134:137], v[12:15]
	s_setprio 0
	s_mov_b32 m0, s77
	v_lshl_add_u64 v[162:163], v[168:169], 0, s[56:57]
	s_barrier
	ds_read_b128 v[114:117], v230 offset:49152
	ds_read_b128 v[118:121], v230 offset:50176
	ds_read_b128 v[122:125], v230 offset:51200
	ds_read_b128 v[126:129], v230 offset:52224
	ds_read_b128 v[130:133], v230 offset:53248
	ds_read_b128 v[134:137], v230 offset:54272
	global_load_lds_dwordx4 v[162:163], off
	v_lshl_add_u64 v[162:163], v[174:175], 0, s[56:57]
	s_mov_b32 m0, s78
	s_nop 0
	global_load_lds_dwordx4 v[162:163], off
	s_barrier
	s_waitcnt lgkmcnt(0)
	s_setprio 1
	s_waitcnt lgkmcnt(0)
	v_mfma_f32_16x16x32_bf16 v[76:79], v[98:101], v[114:117], v[76:79]
	v_mfma_f32_16x16x32_bf16 v[56:59], v[106:109], v[114:117], v[56:59]
	v_mfma_f32_16x16x32_bf16 v[72:75], v[98:101], v[122:125], v[72:75]
	v_mfma_f32_16x16x32_bf16 v[52:55], v[106:109], v[122:125], v[52:55]
	v_mfma_f32_16x16x32_bf16 v[64:67], v[98:101], v[130:133], v[64:67]
	v_mfma_f32_16x16x32_bf16 v[44:47], v[106:109], v[130:133], v[44:47]
	v_mfma_f32_16x16x32_bf16 v[76:79], v[102:105], v[118:121], v[76:79]
	v_mfma_f32_16x16x32_bf16 v[56:59], v[110:113], v[118:121], v[56:59]
	v_mfma_f32_16x16x32_bf16 v[72:75], v[102:105], v[126:129], v[72:75]
	v_mfma_f32_16x16x32_bf16 v[52:55], v[110:113], v[126:129], v[52:55]
	v_mfma_f32_16x16x32_bf16 v[64:67], v[102:105], v[134:137], v[64:67]
	v_mfma_f32_16x16x32_bf16 v[44:47], v[110:113], v[134:137], v[44:47]
	s_setprio 0
	s_barrier
	s_add_u32 s30, s44, 0xb0080
	s_addc_u32 s31, s45, 0
	s_add_i32 s42, s43, s37
	v_lshl_add_u64 v[98:99], s[30:31], 0, v[144:145]
	s_mov_b32 m0, s42
	s_nop 0
	global_load_lds_dwordx4 v[98:99], off
	v_lshl_add_u64 v[98:99], s[30:31], 0, v[142:143]
	s_add_i32 m0, s42, 0x2000
	s_nop 0
	global_load_lds_dwordx4 v[98:99], off
	s_waitcnt vmcnt(6)
	s_barrier
	s_setprio 1
	v_mfma_f32_16x16x32_bf16 v[32:35], v[138:141], v[114:117], v[32:35]
	v_mfma_f32_16x16x32_bf16 v[8:11], v[154:157], v[114:117], v[8:11]
	v_mfma_f32_16x16x32_bf16 v[24:27], v[138:141], v[122:125], v[24:27]
	v_mfma_f32_16x16x32_bf16 v[4:7], v[154:157], v[122:125], v[4:7]
	v_mfma_f32_16x16x32_bf16 v[16:19], v[138:141], v[130:133], v[16:19]
	v_mfma_f32_16x16x32_bf16 v[0:3], v[154:157], v[130:133], v[0:3]
	v_mfma_f32_16x16x32_bf16 v[32:35], v[150:153], v[118:121], v[32:35]
	v_mfma_f32_16x16x32_bf16 v[8:11], v[158:161], v[118:121], v[8:11]
	v_mfma_f32_16x16x32_bf16 v[24:27], v[150:153], v[126:129], v[24:27]
	v_mfma_f32_16x16x32_bf16 v[4:7], v[158:161], v[126:129], v[4:7]
	v_mfma_f32_16x16x32_bf16 v[16:19], v[150:153], v[134:137], v[16:19]
	v_mfma_f32_16x16x32_bf16 v[0:3], v[158:161], v[134:137], v[0:3]
	s_setprio 0
	s_add_i32 s52, s52, 2
	s_add_u32 s50, s50, 0x100
	s_addc_u32 s51, s51, 0
	s_cmp_gt_u32 s52, 41
	s_mov_b64 s[30:31], s[0:1]
	s_barrier

.LBB0_522:
	v_mov_b64_e32 v[0:1], 0x840
	s_ashr_i32 s45, s44, 31
	v_cmp_lt_i64_e32 vcc, s[46:47], v[0:1]
	s_lshl_b64 s[46:47], s[44:45], 19
	s_add_u32 s46, s22, s46
	s_addc_u32 s47, s23, s47
	s_and_b64 s[48:49], vcc, exec
	s_cselect_b32 s45, s47, s31
	s_cselect_b32 s75, s46, s30
	s_ashr_i32 s1, s0, 31
	s_lshl_b64 s[48:49], s[0:1], 19
	s_add_u32 s48, s24, s48
	s_addc_u32 s49, s36, s49
	s_and_b64 s[52:53], vcc, exec
	s_cselect_b32 s1, s49, s51
	s_cselect_b32 s76, s48, s50
	s_add_u32 s30, s30, 0x40080
	s_addc_u32 s31, s31, 0
	s_add_u32 s77, s50, 0x100
	s_addc_u32 s78, s51, 0
	s_mov_b32 s79, -2
	s_add_u32 s42, s30, 0xfffc0080
	s_addc_u32 s43, s31, -1
	s_add_i32 s80, 0, 0x10000
	v_add_u32_e32 v140, s80, v144
	ds_read_b128 v[146:149], v140
	ds_read_b128 v[150:153], v140 offset:1024
	ds_read_b128 v[154:157], v140 offset:2048
	ds_read_b128 v[158:161], v140 offset:3072
	s_cmp_eq_u32 s79, 12
	s_cselect_b32 s53, s45, s43
	s_cselect_b32 s52, s75, s42
	s_cselect_b32 s51, s1, s78
	s_cselect_b32 s50, s76, s77
	v_lshl_add_u64 v[140:141], s[30:31], 0, v[136:137]
	s_add_i32 m0, s58, 0xc000
	ds_read_b128 v[174:177], v145
	ds_read_b128 v[178:181], v145 offset:1024
	ds_read_b128 v[182:185], v145 offset:2048
	ds_read_b128 v[186:189], v145 offset:3072
	ds_read_b128 v[190:193], v145 offset:4096
	ds_read_b128 v[194:197], v145 offset:5120
	ds_read_b128 v[198:201], v145 offset:6144
	ds_read_b128 v[228:231], v145 offset:7168
	global_load_lds_dwordx4 v[140:141], off
	v_lshl_add_u64 v[140:141], s[30:31], 0, v[138:139]
	s_add_i32 m0, s58, 0xe000
	s_nop 0
	global_load_lds_dwordx4 v[140:141], off
	s_waitcnt lgkmcnt(8)
	s_barrier
	s_waitcnt lgkmcnt(0)
	s_setprio 1
	s_waitcnt lgkmcnt(0)
	v_mfma_f32_16x16x32_bf16 v[126:129], v[146:149], v[174:177], 0
	v_mfma_f32_16x16x32_bf16 v[114:117], v[154:157], v[174:177], 0
	v_mfma_f32_16x16x32_bf16 v[110:113], v[146:149], v[182:185], 0
	v_mfma_f32_16x16x32_bf16 v[98:101], v[154:157], v[182:185], 0
	v_mfma_f32_16x16x32_bf16 v[92:95], v[146:149], v[190:193], 0
	v_mfma_f32_16x16x32_bf16 v[80:83], v[154:157], v[190:193], 0
	v_mfma_f32_16x16x32_bf16 v[76:79], v[146:149], v[198:201], 0
	v_mfma_f32_16x16x32_bf16 v[64:67], v[154:157], v[198:201], 0
	v_mfma_f32_16x16x32_bf16 v[126:129], v[150:153], v[178:181], v[126:129]
	v_mfma_f32_16x16x32_bf16 v[114:117], v[158:161], v[178:181], v[114:117]
	v_mfma_f32_16x16x32_bf16 v[110:113], v[150:153], v[186:189], v[110:113]
	v_mfma_f32_16x16x32_bf16 v[98:101], v[158:161], v[186:189], v[98:101]
	v_mfma_f32_16x16x32_bf16 v[92:95], v[150:153], v[194:197], v[92:95]
	v_mfma_f32_16x16x32_bf16 v[80:83], v[158:161], v[194:197], v[80:83]
	v_mfma_f32_16x16x32_bf16 v[76:79], v[150:153], v[228:231], v[76:79]
	v_mfma_f32_16x16x32_bf16 v[64:67], v[158:161], v[228:231], v[64:67]
	s_setprio 0
	s_barrier
	s_add_i32 s42, 0, 0x14000
	v_add_u32_e32 v140, s42, v144
	s_add_i32 s43, s80, s37
	ds_read_b128 v[232:235], v140
	ds_read_b128 v[236:239], v140 offset:1024
	ds_read_b128 v[240:243], v140 offset:2048
	ds_read_b128 v[244:247], v140 offset:3072
	v_lshl_add_u64 v[140:141], s[50:51], 0, v[96:97]
	s_mov_b32 m0, s43
	v_lshl_add_u64 v[162:163], s[50:51], 0, v[130:131]
	global_load_lds_dwordx4 v[140:141], off
	s_add_i32 m0, s43, 0x2000
	s_nop 0
	global_load_lds_dwordx4 v[162:163], off
	s_barrier
	s_waitcnt lgkmcnt(0)
	s_setprio 1
	s_waitcnt lgkmcnt(0)
	v_mfma_f32_16x16x32_bf16 v[122:125], v[232:235], v[174:177], 0
	v_mfma_f32_16x16x32_bf16 v[118:121], v[240:243], v[174:177], 0
	v_mfma_f32_16x16x32_bf16 v[106:109], v[232:235], v[182:185], 0
	v_mfma_f32_16x16x32_bf16 v[102:105], v[240:243], v[182:185], 0
	v_mfma_f32_16x16x32_bf16 v[88:91], v[232:235], v[190:193], 0
	v_mfma_f32_16x16x32_bf16 v[84:87], v[240:243], v[190:193], 0
	v_mfma_f32_16x16x32_bf16 v[72:75], v[232:235], v[198:201], 0
	v_mfma_f32_16x16x32_bf16 v[68:71], v[240:243], v[198:201], 0
	v_mfma_f32_16x16x32_bf16 v[122:125], v[236:239], v[178:181], v[122:125]
	v_mfma_f32_16x16x32_bf16 v[118:121], v[244:247], v[178:181], v[118:121]
	v_mfma_f32_16x16x32_bf16 v[106:109], v[236:239], v[186:189], v[106:109]
	v_mfma_f32_16x16x32_bf16 v[102:105], v[244:247], v[186:189], v[102:105]
	v_mfma_f32_16x16x32_bf16 v[88:91], v[236:239], v[194:197], v[88:91]
	v_mfma_f32_16x16x32_bf16 v[84:87], v[244:247], v[194:197], v[84:87]
	v_mfma_f32_16x16x32_bf16 v[72:75], v[236:239], v[228:231], v[72:75]
	v_mfma_f32_16x16x32_bf16 v[68:71], v[244:247], v[228:231], v[68:71]
	s_setprio 0
	s_mov_b32 m0, s58
	v_lshl_add_u64 v[166:167], s[52:53], 0, v[134:135]
	s_barrier
	ds_read_b128 v[174:177], v145 offset:16384
	ds_read_b128 v[178:181], v145 offset:17408
	ds_read_b128 v[182:185], v145 offset:18432
	ds_read_b128 v[186:189], v145 offset:19456
	ds_read_b128 v[190:193], v145 offset:20480
	ds_read_b128 v[194:197], v145 offset:21504
	ds_read_b128 v[198:201], v145 offset:22528
	ds_read_b128 v[228:231], v145 offset:23552
	global_load_lds_dwordx4 v[166:167], off
	v_lshl_add_u64 v[168:169], s[52:53], 0, v[132:133]
	s_mov_b32 m0, s59
	s_nop 0
	global_load_lds_dwordx4 v[168:169], off
	s_barrier
	s_waitcnt lgkmcnt(0)
	s_setprio 1
	s_waitcnt lgkmcnt(0)
	v_mfma_f32_16x16x32_bf16 v[60:63], v[146:149], v[174:177], 0
	v_mfma_f32_16x16x32_bf16 v[48:51], v[154:157], v[174:177], 0
	v_mfma_f32_16x16x32_bf16 v[44:47], v[146:149], v[182:185], 0
	v_mfma_f32_16x16x32_bf16 v[32:35], v[154:157], v[182:185], 0
	v_mfma_f32_16x16x32_bf16 v[28:31], v[146:149], v[190:193], 0
	v_mfma_f32_16x16x32_bf16 v[16:19], v[154:157], v[190:193], 0
	v_mfma_f32_16x16x32_bf16 v[12:15], v[146:149], v[198:201], 0
	v_mfma_f32_16x16x32_bf16 v[4:7], v[154:157], v[198:201], 0
	v_mfma_f32_16x16x32_bf16 v[60:63], v[150:153], v[178:181], v[60:63]
	v_mfma_f32_16x16x32_bf16 v[48:51], v[158:161], v[178:181], v[48:51]
	v_mfma_f32_16x16x32_bf16 v[44:47], v[150:153], v[186:189], v[44:47]
	v_mfma_f32_16x16x32_bf16 v[32:35], v[158:161], v[186:189], v[32:35]
	v_mfma_f32_16x16x32_bf16 v[28:31], v[150:153], v[194:197], v[28:31]
	v_mfma_f32_16x16x32_bf16 v[16:19], v[158:161], v[194:197], v[16:19]
	v_mfma_f32_16x16x32_bf16 v[12:15], v[150:153], v[228:231], v[12:15]
	v_mfma_f32_16x16x32_bf16 v[4:7], v[158:161], v[228:231], v[4:7]
	s_setprio 0
	s_barrier
	s_add_u32 s80, s50, 0x40000
	s_addc_u32 s81, s51, 0
	s_add_i32 s42, s42, s37
	v_lshl_add_u64 v[146:147], s[80:81], 0, v[96:97]
	s_mov_b32 m0, s42
	s_nop 0
	global_load_lds_dwordx4 v[146:147], off
	v_lshl_add_u64 v[146:147], s[80:81], 0, v[130:131]
	s_add_i32 m0, s42, 0x2000
	s_nop 0
	global_load_lds_dwordx4 v[146:147], off
	s_waitcnt vmcnt(6)
	s_barrier
	s_setprio 1
	v_mfma_f32_16x16x32_bf16 v[56:59], v[232:235], v[174:177], 0
	v_mfma_f32_16x16x32_bf16 v[52:55], v[240:243], v[174:177], 0
	v_mfma_f32_16x16x32_bf16 v[40:43], v[232:235], v[182:185], 0
	v_mfma_f32_16x16x32_bf16 v[36:39], v[240:243], v[182:185], 0
	v_mfma_f32_16x16x32_bf16 v[24:27], v[232:235], v[190:193], 0
	v_mfma_f32_16x16x32_bf16 v[20:23], v[240:243], v[190:193], 0
	v_mfma_f32_16x16x32_bf16 v[8:11], v[232:235], v[198:201], 0
	v_mfma_f32_16x16x32_bf16 v[0:3], v[240:243], v[198:201], 0
	v_mfma_f32_16x16x32_bf16 v[56:59], v[236:239], v[178:181], v[56:59]
	v_mfma_f32_16x16x32_bf16 v[52:55], v[244:247], v[178:181], v[52:55]
	v_mfma_f32_16x16x32_bf16 v[40:43], v[236:239], v[186:189], v[40:43]
	v_mfma_f32_16x16x32_bf16 v[36:39], v[244:247], v[186:189], v[36:39]
	v_mfma_f32_16x16x32_bf16 v[24:27], v[236:239], v[194:197], v[24:27]
	v_mfma_f32_16x16x32_bf16 v[20:23], v[244:247], v[194:197], v[20:23]
	v_mfma_f32_16x16x32_bf16 v[8:11], v[236:239], v[228:231], v[8:11]
	v_mfma_f32_16x16x32_bf16 v[0:3], v[244:247], v[228:231], v[0:3]
	s_setprio 0
	s_add_i32 s42, 0, 0x18000
	v_add_u32_e32 v158, s42, v144
	s_barrier
	ds_read_b128 v[146:149], v158
	ds_read_b128 v[150:153], v158 offset:1024
	ds_read_b128 v[154:157], v158 offset:2048
	ds_read_b128 v[158:161], v158 offset:3072
	s_add_u32 s52, s52, 0x40000
	s_addc_u32 s53, s53, 0
	s_mov_b32 m0, s60
	v_lshl_add_u64 v[202:203], s[52:53], 0, v[134:135]
	ds_read_b128 v[174:177], v145 offset:32768
	ds_read_b128 v[178:181], v145 offset:33792
	ds_read_b128 v[182:185], v145 offset:34816
	ds_read_b128 v[186:189], v145 offset:35840
	ds_read_b128 v[190:193], v145 offset:36864
	ds_read_b128 v[194:197], v145 offset:37888
	ds_read_b128 v[198:201], v145 offset:38912
	ds_read_b128 v[228:231], v145 offset:39936
	global_load_lds_dwordx4 v[202:203], off
	v_lshl_add_u64 v[202:203], s[52:53], 0, v[132:133]
	s_mov_b32 m0, s61
	s_nop 0
	global_load_lds_dwordx4 v[202:203], off
	s_waitcnt lgkmcnt(8)
	s_barrier
	s_waitcnt lgkmcnt(0)
	s_setprio 1
	s_waitcnt lgkmcnt(0)
	v_mfma_f32_16x16x32_bf16 v[126:129], v[146:149], v[174:177], v[126:129]
	v_mfma_f32_16x16x32_bf16 v[114:117], v[154:157], v[174:177], v[114:117]
	v_mfma_f32_16x16x32_bf16 v[110:113], v[146:149], v[182:185], v[110:113]
	v_mfma_f32_16x16x32_bf16 v[98:101], v[154:157], v[182:185], v[98:101]
	v_mfma_f32_16x16x32_bf16 v[92:95], v[146:149], v[190:193], v[92:95]
	v_mfma_f32_16x16x32_bf16 v[80:83], v[154:157], v[190:193], v[80:83]
	v_mfma_f32_16x16x32_bf16 v[76:79], v[146:149], v[198:201], v[76:79]
	v_mfma_f32_16x16x32_bf16 v[64:67], v[154:157], v[198:201], v[64:67]
	v_mfma_f32_16x16x32_bf16 v[126:129], v[150:153], v[178:181], v[126:129]
	v_mfma_f32_16x16x32_bf16 v[114:117], v[158:161], v[178:181], v[114:117]
	v_mfma_f32_16x16x32_bf16 v[110:113], v[150:153], v[186:189], v[110:113]
	v_mfma_f32_16x16x32_bf16 v[98:101], v[158:161], v[186:189], v[98:101]
	v_mfma_f32_16x16x32_bf16 v[92:95], v[150:153], v[194:197], v[92:95]
	v_mfma_f32_16x16x32_bf16 v[80:83], v[158:161], v[194:197], v[80:83]
	v_mfma_f32_16x16x32_bf16 v[76:79], v[150:153], v[228:231], v[76:79]
	v_mfma_f32_16x16x32_bf16 v[64:67], v[158:161], v[228:231], v[64:67]
	s_setprio 0
	s_barrier
	s_add_i32 s43, 0, 0x1c000
	s_add_i32 s42, s42, s37
	v_add_u32_e32 v164, s43, v144
	v_lshl_add_u64 v[140:141], v[140:141], 0, s[56:57]
	s_mov_b32 m0, s42
	ds_read_b128 v[232:235], v164
	ds_read_b128 v[236:239], v164 offset:1024
	ds_read_b128 v[240:243], v164 offset:2048
	ds_read_b128 v[244:247], v164 offset:3072
	global_load_lds_dwordx4 v[140:141], off
	v_lshl_add_u64 v[140:141], v[162:163], 0, s[56:57]
	s_add_i32 m0, s42, 0x2000
	s_nop 0
	global_load_lds_dwordx4 v[140:141], off
	s_barrier
	s_waitcnt lgkmcnt(0)
	s_setprio 1
	s_waitcnt lgkmcnt(0)
	v_mfma_f32_16x16x32_bf16 v[122:125], v[232:235], v[174:177], v[122:125]
	v_mfma_f32_16x16x32_bf16 v[118:121], v[240:243], v[174:177], v[118:121]
	v_mfma_f32_16x16x32_bf16 v[106:109], v[232:235], v[182:185], v[106:109]
	v_mfma_f32_16x16x32_bf16 v[102:105], v[240:243], v[182:185], v[102:105]
	v_mfma_f32_16x16x32_bf16 v[88:91], v[232:235], v[190:193], v[88:91]
	v_mfma_f32_16x16x32_bf16 v[84:87], v[240:243], v[190:193], v[84:87]
	v_mfma_f32_16x16x32_bf16 v[72:75], v[232:235], v[198:201], v[72:75]
	v_mfma_f32_16x16x32_bf16 v[68:71], v[240:243], v[198:201], v[68:71]
	v_mfma_f32_16x16x32_bf16 v[122:125], v[236:239], v[178:181], v[122:125]
	v_mfma_f32_16x16x32_bf16 v[118:121], v[244:247], v[178:181], v[118:121]
	v_mfma_f32_16x16x32_bf16 v[106:109], v[236:239], v[186:189], v[106:109]
	v_mfma_f32_16x16x32_bf16 v[102:105], v[244:247], v[186:189], v[102:105]
	v_mfma_f32_16x16x32_bf16 v[88:91], v[236:239], v[194:197], v[88:91]
	v_mfma_f32_16x16x32_bf16 v[84:87], v[244:247], v[194:197], v[84:87]
	v_mfma_f32_16x16x32_bf16 v[72:75], v[236:239], v[228:231], v[72:75]
	v_mfma_f32_16x16x32_bf16 v[68:71], v[244:247], v[228:231], v[68:71]
	s_setprio 0
	s_mov_b32 m0, s70
	v_lshl_add_u64 v[140:141], v[166:167], 0, s[56:57]
	s_barrier
	ds_read_b128 v[174:177], v145 offset:49152
	ds_read_b128 v[178:181], v145 offset:50176
	ds_read_b128 v[182:185], v145 offset:51200
	ds_read_b128 v[186:189], v145 offset:52224
	ds_read_b128 v[190:193], v145 offset:53248
	ds_read_b128 v[194:197], v145 offset:54272
	ds_read_b128 v[198:201], v145 offset:55296
	ds_read_b128 v[228:231], v145 offset:56320
	global_load_lds_dwordx4 v[140:141], off
	v_lshl_add_u64 v[140:141], v[168:169], 0, s[56:57]
	s_mov_b32 m0, s71
	s_nop 0
	global_load_lds_dwordx4 v[140:141], off
	s_barrier
	s_waitcnt lgkmcnt(0)
	s_setprio 1
	s_waitcnt lgkmcnt(0)
	v_mfma_f32_16x16x32_bf16 v[60:63], v[146:149], v[174:177], v[60:63]
	v_mfma_f32_16x16x32_bf16 v[48:51], v[154:157], v[174:177], v[48:51]
	v_mfma_f32_16x16x32_bf16 v[44:47], v[146:149], v[182:185], v[44:47]
	v_mfma_f32_16x16x32_bf16 v[32:35], v[154:157], v[182:185], v[32:35]
	v_mfma_f32_16x16x32_bf16 v[28:31], v[146:149], v[190:193], v[28:31]
	v_mfma_f32_16x16x32_bf16 v[16:19], v[154:157], v[190:193], v[16:19]
	v_mfma_f32_16x16x32_bf16 v[12:15], v[146:149], v[198:201], v[12:15]
	v_mfma_f32_16x16x32_bf16 v[4:7], v[154:157], v[198:201], v[4:7]
	v_mfma_f32_16x16x32_bf16 v[60:63], v[150:153], v[178:181], v[60:63]
	v_mfma_f32_16x16x32_bf16 v[48:51], v[158:161], v[178:181], v[48:51]
	v_mfma_f32_16x16x32_bf16 v[44:47], v[150:153], v[186:189], v[44:47]
	v_mfma_f32_16x16x32_bf16 v[32:35], v[158:161], v[186:189], v[32:35]
	v_mfma_f32_16x16x32_bf16 v[28:31], v[150:153], v[194:197], v[28:31]
	v_mfma_f32_16x16x32_bf16 v[16:19], v[158:161], v[194:197], v[16:19]
	v_mfma_f32_16x16x32_bf16 v[12:15], v[150:153], v[228:231], v[12:15]
	v_mfma_f32_16x16x32_bf16 v[4:7], v[158:161], v[228:231], v[4:7]
	s_setprio 0
	s_barrier
	s_add_u32 s50, s50, 0x40080
	s_addc_u32 s51, s51, 0
	s_add_i32 s42, s43, s37
	v_lshl_add_u64 v[140:141], s[50:51], 0, v[96:97]
	s_mov_b32 m0, s42
	s_nop 0
	global_load_lds_dwordx4 v[140:141], off
	v_lshl_add_u64 v[140:141], s[50:51], 0, v[130:131]
	s_add_i32 m0, s42, 0x2000
	s_nop 0
	global_load_lds_dwordx4 v[140:141], off
	s_waitcnt vmcnt(6)
	s_barrier
	s_setprio 1
	v_mfma_f32_16x16x32_bf16 v[56:59], v[232:235], v[174:177], v[56:59]
	v_mfma_f32_16x16x32_bf16 v[52:55], v[240:243], v[174:177], v[52:55]
	v_mfma_f32_16x16x32_bf16 v[40:43], v[232:235], v[182:185], v[40:43]
	v_mfma_f32_16x16x32_bf16 v[36:39], v[240:243], v[182:185], v[36:39]
	v_mfma_f32_16x16x32_bf16 v[24:27], v[232:235], v[190:193], v[24:27]
	v_mfma_f32_16x16x32_bf16 v[20:23], v[240:243], v[190:193], v[20:23]
	v_mfma_f32_16x16x32_bf16 v[8:11], v[232:235], v[198:201], v[8:11]
	v_mfma_f32_16x16x32_bf16 v[0:3], v[240:243], v[198:201], v[0:3]
	v_mfma_f32_16x16x32_bf16 v[56:59], v[236:239], v[178:181], v[56:59]
	v_mfma_f32_16x16x32_bf16 v[52:55], v[244:247], v[178:181], v[52:55]
	v_mfma_f32_16x16x32_bf16 v[40:43], v[236:239], v[186:189], v[40:43]
	v_mfma_f32_16x16x32_bf16 v[36:39], v[244:247], v[186:189], v[36:39]
	v_mfma_f32_16x16x32_bf16 v[24:27], v[236:239], v[194:197], v[24:27]
	v_mfma_f32_16x16x32_bf16 v[20:23], v[244:247], v[194:197], v[20:23]
	v_mfma_f32_16x16x32_bf16 v[8:11], v[236:239], v[228:231], v[8:11]
	v_mfma_f32_16x16x32_bf16 v[0:3], v[244:247], v[228:231], v[0:3]
	s_setprio 0
	s_add_i32 s79, s79, 2
	s_add_u32 s30, s30, 0x100
	s_addc_u32 s31, s31, 0
	s_add_u32 s77, s77, 0x100
	s_addc_u32 s78, s78, 0
	s_cmp_gt_u32 s79, 13
	s_barrier
